# static s_setprio 1 for waves 4-7 during GQA attention units (desynchronise SIMD wave pairs)
# speedup vs baseline: 1.0085x; 1.0085x over previous
;     const int tid = opaque_tid(), lane = tid & 63, r32 = lane & 31, hi = lane >> 5; const int wid = __builtin_amdgcn_readfirstlane(tid >> 6);
;     const bf16_t* Qw = Q + (long)(wid * QBLK) * PITCH;
;     const unsigned lds0 = (unsigned)(uintptr_t)shm;
;     float* wsf = (float*)(shm + LDS_WS) + wid * 64;
;     const unsigned kvo = (unsigned)((lane * PITCH + wid * 8) * 2);
;     const unsigned vvo = (unsigned)(((16 * (wid & 3) + (lane >> 2)) * PITCH + (wid >> 2) * 32 + (lane & 3) * 8) * 2);
;     const unsigned kdst = lds0 + LDS_K + wid * 1024, vdst = lds0 + LDS_V + wid * 1024;
;     ...
;     const char* Kbase = shm + LDS_K; bf16x8 kf[8];
;     const lds_cptr shm3 = (lds_cptr)shm; const lds_cptr kp0 = shm3 + LDS_K + hi * 1024 + r32 * 16; const lds_cptr vp0 = shm3 + LDS_V + ((lane >> 4) & 1) * 32 + (lane & 3) * 8 + (4 * hi + ((lane & 15) >> 2)) * 64;
;     DMA_K(0, 0); DMA_V(0, 0); DMA_K(1, SLOTB);
;     bf16x8 qr[4];
; #pragma unroll
;     for (int d0 = 0; d0 < 4; ++d0) qr[d0] = *reinterpret_cast<const bf16x8*>(&Qw[(long)r32 * PITCH + d0 * 16 + hi * 8]);
;     float mhat = (MODE == 0) ? bref : 0.f, l_reg = 0.f; f32x16 o[2]; o[0] = f32x16{}; o[1] = f32x16{}; f32x16 negm = f32x16{};
;     if (MODE == 0) { _Pragma("unroll") for (int r = 0; r < 16; ++r) negm[r] = -bref; }
;     if (MODE != 1) asm volatile("" : "+v"(negm));
;     int na_gr = 0, na_rs = 0, na_qc = 0, na_cs = 0;
;     if (MODE == 1) { na_gr = r0 + (wid >> 1); na_rs = min(max(na_gr - 4, 0), 120); na_qc = 32 * (wid & 1) + r32; na_cs = min(max(na_qc - 8, 0), 48); }
;     ...
;     bool resc = false;
;     ...
;     f32x16 pA0, pA1, pB0, pB1;
;     int sl_prev = 0, sl_cur = 0, sl_next = SLOTB;
;     ...
;     DMA_K(2, 2 * SLOTB);
;     WAIT_BAR(3);
;     qkt(pA0, pA1, Kbase, qr, negm, r32, hi); asm volatile("s_nop 15\n\ts_nop 7" : "+v"(pA0), "+v"(pA1));
;     START(pA0, pA1);
; __global__ void __launch_bounds__(NTHREADS, 2) mega_fwd(Params P) {
;     ...
;                     const int qb = idx / 12, r12 = idx % 12, b = r12 / 6, h = r12 % 6; const size_t rb = (size_t)b * RPB;
;                     ap::unit<8, 0>(qkv + (rb + 256 * qb) * DIN + C_QC + 64 * h, qkv + rb * DIN + C_KC + 64 * (h / 3), qkv + rb * DIN + C_VC + 64 * (h / 3),
;                                    omix + (rb + 256 * qb) * DM + 640 + 64 * h, ssb + (rb + 256 * qb) * 4 + 2, 132, (char*)lds, 0, 0, tcos[4096 + l]);
.LBB0_874:
	s_andn2_b64 vcc, exec, s[0:1]
	s_cbranch_vccnz .LBB0_439
	s_mul_hi_i32 s0, s48, 0x2aaaaaab
	s_lshr_b32 s1, s0, 31
	s_ashr_i32 s3, s0, 1
	s_add_i32 s3, s3, s1
	s_mul_i32 s0, s3, 12
	s_sub_i32 s0, s48, s0
	s_mul_i32 s1, s0, 43
	s_bfe_u32 s2, s1, 0x1000f
	s_bfe_u32 s1, s1, 0x80008
	s_add_i32 s1, s1, s2
	s_sext_i32_i8 s18, s1
	s_mul_i32 s1, s1, 6
	s_mul_i32 s9, s18, 0x2100
	s_lshl_b32 s4, s3, 8
	s_sub_i32 s8, s0, s1
	s_ashr_i32 s5, s9, 31
	s_ashr_i32 s6, s4, 31
	s_add_u32 s4, s9, s4
	s_addc_u32 s5, s5, s6
	s_mul_i32 s6, s5, 0x1200
	s_mul_hi_u32 s7, s4, 0x1200
	s_mov_b64 s[0:1], s[76:77]
	s_add_i32 s7, s7, s6
	s_mul_i32 s6, s4, 0x1200
	s_sext_i32_i8 s2, s8
	s_add_u32 s10, s0, s6
	s_addc_u32 s11, s1, s7
	s_lshl_b32 s0, s2, 6
	s_ashr_i32 s1, s0, 31
	s_lshl_b64 s[6:7], s[0:1], 1
	s_add_u32 s26, s10, s6
	s_addc_u32 s27, s11, s7
	s_mov_b64 s[0:1], s[76:77]
	s_mul_i32 s10, s18, 0x2520000
	s_mul_hi_i32 s9, s9, 0x1200
	s_add_u32 s2, s0, s10
	s_addc_u32 s22, s1, s9
	s_bfe_i32 s0, s8, 0x80000
	s_mulk_i32 s0, 0x56
	s_bfe_u32 s1, s0, 0x1000f
	s_bfe_u32 s0, s0, 0x80008
	s_add_i32 s0, s0, s1
	s_sext_i32_i8 s0, s0
	s_lshl_b32 s0, s0, 6
	s_ashr_i32 s1, s0, 31
	s_lshl_b64 s[16:17], s[0:1], 1
	s_add_u32 s30, s2, s16
	s_addc_u32 s34, s22, s17
	s_add_u32 s14, s30, 0xe400300
	s_addc_u32 s15, s34, 0
	s_mov_b64 s[0:1], s[76:77]
	s_add_u32 s23, s0, s10
	s_addc_u32 s24, s1, s9
	s_add_u32 s35, s23, s16
	s_addc_u32 s36, s24, s17
	v_readlane_b32 s20, v252, 9
	s_add_u32 s12, s35, 0xe401100
	s_mov_b64 s[10:11], s[76:77]
	s_mov_b64 s[8:9], s[76:77]
	s_mov_b64 s[0:1], s[76:77]
	v_readlane_b32 s21, v252, 10
	s_addc_u32 s13, s36, 0
	s_lshl_b64 s[20:21], s[20:21], 2
	s_add_u32 s0, s0, s20
	s_addc_u32 s1, s1, s21
	v_mov_b32_e32 v0, s0
	s_mov_b32 s0, 0x184000
	v_mov_b32_e32 v3, s1
	v_add_co_u32_e32 v2, vcc, s0, v0
	v_mov_b32_e32 v194, 0
	s_nop 0
	v_addc_co_u32_e32 v3, vcc, 0, v3, vcc
	flat_load_dword v6, v[2:3]
	v_mov_b32 v14, v214
	s_waitcnt vmcnt(0) lgkmcnt(0)
	v_xor_b32_e32 v50, 0x80000000, v6
	v_readfirstlane_b32 s25, v14
	s_ashr_i32 s19, s25, 6
	s_cmp_ge_u32 s19, 4
	s_cbranch_scc0 .Lgqa_prio_skip
	s_setprio 1
.Lgqa_prio_skip:
	s_lshl_b32 s0, s19, 5
	s_ashr_i32 s1, s0, 31
	s_mul_i32 s20, s19, 0x24000
	s_mul_hi_i32 s21, s0, 0x1200
	s_add_u32 s28, s26, s20
	s_addc_u32 s29, s27, s21
	s_lshl_b32 s20, s19, 4
	v_and_b32_e32 v15, 63, v14
	v_mov_b32_e32 v0, s20
	v_mad_u32_u24 v193, v15, s80, v0
	v_bfe_u32 v0, v14, 2, 4
	v_and_or_b32 v0, s20, 48, v0
	s_ashr_i32 s20, s25, 3
	s_and_b32 s20, s20, 0x7fffffe0
	v_mov_b32_e32 v2, s20
	v_mad_u32_u24 v0, v0, s81, v2
	v_lshlrev_b32_e32 v2, 3, v14
	v_and_b32_e32 v187, 24, v2
	v_and_b32_e32 v17, 31, v14
	v_or_b32_e32 v0, v0, v187
	s_lshl_b32 s21, s19, 10
	v_lshlrev_b32_e32 v192, 1, v0
	s_cmp_lg_u32 0, -1
	v_mul_u32_u24_e32 v0, 0x900, v17
	v_bfe_u32 v186, v14, 5, 1
	s_cselect_b32 s20, 0, 0
	v_lshlrev_b32_e32 v0, 1, v0
	s_add_i32 s26, s21, s20
	v_lshl_or_b32 v0, v186, 4, v0
	s_add_i32 s20, s26, 0x6000
	s_mov_b32 s27, m0
	s_mov_b32 m0, s26
	s_nop 0
	global_load_lds_dwordx4 v193, s[14:15]
	s_mov_b32 m0, s27
	v_lshl_add_u64 v[2:3], s[28:29], 0, v[0:1]
	s_mov_b32 s27, m0
	s_mov_b32 m0, s20
	s_nop 0
	global_load_lds_dwordx4 v192, s[12:13]
	s_mov_b32 m0, s27
	s_add_u32 s38, s30, 0xe448300
	v_add_co_u32_e32 v4, vcc, s82, v2
	s_addc_u32 s39, s34, 0
	s_add_i32 s27, s26, 0x2000
	s_mov_b32 s31, m0
	s_mov_b32 m0, s27
	s_nop 0
	global_load_lds_dwordx4 v193, s[38:39]
	s_mov_b32 m0, s31
	v_addc_co_u32_e32 v5, vcc, 0, v3, vcc
	flat_load_dwordx4 v[162:165], v[4:5]
	s_mov_b64 s[28:29], 0xe400000
	v_lshl_add_u64 v[2:3], v[2:3], 0, s[28:29]
	flat_load_dwordx4 v[158:161], v[2:3] offset:32
	flat_load_dwordx4 v[154:157], v[2:3] offset:64
	flat_load_dwordx4 v[150:153], v[2:3] offset:96
	v_mov_b32_e32 v51, v50
	v_mov_b32_e32 v52, v50
	v_mov_b32_e32 v53, v50
	v_mov_b32_e32 v54, v50
	v_mov_b32_e32 v55, v50
	v_mov_b32_e32 v56, v50
	v_mov_b32_e32 v57, v50
	v_mov_b32_e32 v58, v50
	v_mov_b32_e32 v59, v50
	v_mov_b32_e32 v60, v50
	v_mov_b32_e32 v61, v50
	v_mov_b32_e32 v62, v50
	v_mov_b32_e32 v63, v50
	v_mov_b32_e32 v64, v50
	v_mov_b32_e32 v65, v50
	s_add_u32 s28, s30, 0xe490300
	v_lshlrev_b32_e32 v0, 10, v186
	v_lshlrev_b32_e32 v4, 4, v17
	s_addc_u32 s29, s34, 0
	s_add_i32 s27, s26, 0x4000
	s_mov_b32 s31, m0
	s_mov_b32 m0, s27
	s_nop 0
	global_load_lds_dwordx4 v193, s[28:29]
	s_mov_b32 m0, s31
	v_add3_u32 v191, 0, v0, v4
	s_waitcnt vmcnt(3) lgkmcnt(0)
	s_barrier
	ds_read_b128 v[2:5], v191
	ds_read_b128 v[6:9], v191 offset:512
	s_waitcnt vmcnt(0) lgkmcnt(0)
	v_mfma_f32_32x32x16_bf16 v[34:49], v[2:5], v[162:165], v[50:65]
	s_add_u32 s38, s30, 0xe4d8300
	s_addc_u32 s39, s34, 0
	s_add_u32 s34, s35, 0xe449100
	s_addc_u32 s35, s36, 0
	v_lshlrev_b32_e32 v0, 1, v14
	v_and_b32_e32 v188, 32, v0
	v_lshlrev_b32_e32 v0, 8, v186
	v_mfma_f32_32x32x16_bf16 v[18:33], v[6:9], v[162:165], v[50:65]
	ds_read_b128 v[2:5], v191 offset:2048
	ds_read_b128 v[6:9], v191 offset:2560
	s_mov_b32 s31, 0
	s_mov_b32 s27, -1
	s_movk_i32 s29, 0x2000
	s_movk_i32 s28, 0x4000
	s_waitcnt lgkmcnt(1)
	v_mfma_f32_32x32x16_bf16 v[34:49], v[2:5], v[158:161], v[34:49]
	s_waitcnt lgkmcnt(0)
	v_mfma_f32_32x32x16_bf16 v[18:33], v[6:9], v[158:161], v[18:33]
	ds_read_b128 v[2:5], v191 offset:4096
	ds_read_b128 v[6:9], v191 offset:4608
	s_waitcnt lgkmcnt(1)
	v_mfma_f32_32x32x16_bf16 v[34:49], v[2:5], v[154:157], v[34:49]
	s_waitcnt lgkmcnt(0)
	v_mfma_f32_32x32x16_bf16 v[18:33], v[6:9], v[154:157], v[18:33]
	ds_read_b128 v[2:5], v191 offset:6144
	ds_read_b128 v[6:9], v191 offset:6656
	s_waitcnt lgkmcnt(1)
	v_mfma_f32_32x32x16_bf16 v[34:49], v[2:5], v[150:153], v[34:49]
	v_lshlrev_b32_e32 v3, 4, v14
	v_add_u32_e32 v2, 0, v188
	v_and_or_b32 v189, v3, s83, v0
	v_add3_u32 v190, v2, v187, v189
	s_waitcnt lgkmcnt(0)
	v_mfma_f32_32x32x16_bf16 v[18:33], v[6:9], v[150:153], v[18:33]
	s_nop 15
	s_nop 7
	s_waitcnt vmcnt(0) lgkmcnt(0)
	s_barrier
; #define WAIT_BAR(N) asm volatile("s_waitcnt vmcnt(" #N ") lgkmcnt(0)\n\ts_barrier" ::: "memory")
; #define DMA_K(t, slot) glds16s(kvo, Kh + (long)TROW(t) * PITCH, (unsigned)__builtin_amdgcn_readfirstlane(kdst + (slot)))
; #define DMA_V(t, slot) glds16s(vvo, Vh + (long)TROW(t) * PITCH, (unsigned)__builtin_amdgcn_readfirstlane(vdst + (slot)))
; #define ROT() do { sl_prev = sl_cur; sl_cur = sl_next; sl_next = (sl_next == (NSLOT - 1) * SLOTB) ? 0 : sl_next + SLOTB; } while (0)
;     ...
;     _Pragma("unroll") for (int r = 0; r < 16; ++r) pA1[r] = __builtin_amdgcn_exp2f(pA1[r]);
;     WAIT_BAR(0);
;     DMA_K(3, 0); DMA_V(1, SLOTB);
;     ROT();
;     kload8(kf, kp0 + sl_cur);
;     WAIT_BAR(2);
	s_mov_b32 s30, m0
	s_mov_b32 m0, s26
	s_nop 0
	global_load_lds_dwordx4 v193, s[38:39]
	s_mov_b32 m0, s30
	s_add_i32 s30, s26, 0x8000
	s_mov_b32 s36, m0
	s_mov_b32 m0, s30
	s_nop 0
	global_load_lds_dwordx4 v192, s[34:35]
	s_mov_b32 m0, s36
	ds_read_b128 v[98:101], v191 offset:8192
	ds_read_b128 v[170:173], v191 offset:8704
	ds_read_b128 v[174:177], v191 offset:10240
	ds_read_b128 v[166:169], v191 offset:10752
	ds_read_b128 v[142:145], v191 offset:12288
	ds_read_b128 v[138:141], v191 offset:12800
	ds_read_b128 v[134:137], v191 offset:14336
	ds_read_b128 v[130:133], v191 offset:14848
	v_exp_f32_e32 v82, v34
	v_exp_f32_e32 v83, v35
	v_exp_f32_e32 v84, v36
	v_exp_f32_e32 v85, v37
	v_exp_f32_e32 v86, v38
	v_exp_f32_e32 v87, v39
	v_exp_f32_e32 v88, v40
	v_exp_f32_e32 v89, v41
	v_exp_f32_e32 v90, v42
	v_exp_f32_e32 v91, v43
	v_exp_f32_e32 v92, v44
	v_exp_f32_e32 v93, v45
	v_exp_f32_e32 v94, v46
	v_exp_f32_e32 v95, v47
	v_exp_f32_e32 v96, v48
	v_exp_f32_e32 v97, v49
	v_exp_f32_e32 v66, v18
	v_exp_f32_e32 v67, v19
	v_exp_f32_e32 v68, v20
	v_exp_f32_e32 v69, v21
	v_exp_f32_e32 v70, v22
	v_exp_f32_e32 v71, v23
	v_exp_f32_e32 v72, v24
	v_exp_f32_e32 v73, v25
	v_exp_f32_e32 v74, v26
	v_exp_f32_e32 v75, v27
	v_exp_f32_e32 v76, v28
	v_exp_f32_e32 v77, v29
	v_exp_f32_e32 v78, v30
	v_exp_f32_e32 v79, v31
	v_exp_f32_e32 v80, v32
	v_exp_f32_e32 v81, v33
	s_waitcnt vmcnt(2) lgkmcnt(0)
	s_barrier
	v_mov_b32_e32 v18, 0
	v_mov_b32_e32 v19, v194
	v_mov_b32_e32 v20, v194
	v_mov_b32_e32 v21, v194
	v_mov_b32_e32 v22, v194
	v_mov_b32_e32 v23, v194
	v_mov_b32_e32 v24, v194
	v_mov_b32_e32 v25, v194
	v_mov_b32_e32 v26, v194
	v_mov_b32_e32 v27, v194
	v_mov_b32_e32 v28, v194
	v_mov_b32_e32 v29, v194
	v_mov_b32_e32 v30, v194
	v_mov_b32_e32 v31, v194
	v_mov_b32_e32 v32, v194
	v_mov_b32_e32 v33, v194
	v_mov_b32_e32 v34, 0
	v_mov_b32_e32 v35, v194
	v_mov_b32_e32 v36, v194
	v_mov_b32_e32 v37, v194
	v_mov_b32_e32 v38, v194
	v_mov_b32_e32 v39, v194
	v_mov_b32_e32 v40, v194
	v_mov_b32_e32 v41, v194
	v_mov_b32_e32 v42, v194
	v_mov_b32_e32 v43, v194
	v_mov_b32_e32 v44, v194
	v_mov_b32_e32 v45, v194
	v_mov_b32_e32 v46, v194
	v_mov_b32_e32 v47, v194
	v_mov_b32_e32 v48, v194
	v_mov_b32_e32 v49, v194
.LBB0_876:
	v_add_u32_e32 v195, s31, v190
	ds_read_b64_tr_b16 v[182:183], v195 offset:24576
	ds_read_b64_tr_b16 v[184:185], v195 offset:25088
	v_add_f32_e32 v2, v82, v83
	v_add_f32_e32 v2, v84, v2
	v_add_f32_e32 v2, v85, v2
	v_add_f32_e32 v2, v86, v2
	v_add_f32_e32 v2, v87, v2
	v_cvt_pk_bf16_f32 v146, v82, v83
	v_cvt_pk_bf16_f32 v147, v84, v85
	s_waitcnt lgkmcnt(9)
	v_mfma_f32_32x32x16_bf16 v[114:129], v[98:101], v[162:165], v[50:65]
	ds_read_b64_tr_b16 v[178:179], v195 offset:28672
	ds_read_b64_tr_b16 v[180:181], v195 offset:29184
	s_waitcnt lgkmcnt(10)
	v_mfma_f32_32x32x16_bf16 v[98:113], v[170:173], v[162:165], v[50:65]
	v_add_f32_e32 v2, v88, v2
	v_add_f32_e32 v2, v89, v2
	v_add_f32_e32 v2, v90, v2
	v_add_f32_e32 v2, v91, v2
	v_cvt_pk_bf16_f32 v148, v86, v87
	v_cvt_pk_bf16_f32 v149, v88, v89
	ds_read_b64_tr_b16 v[82:83], v195 offset:25600
	ds_read_b64_tr_b16 v[84:85], v195 offset:26112
	v_add_f32_e32 v2, v92, v2
	v_add_f32_e32 v2, v93, v2
	v_add_f32_e32 v2, v94, v2
	v_add_f32_e32 v2, v95, v2
	v_cvt_pk_bf16_f32 v10, v90, v91
	v_cvt_pk_bf16_f32 v11, v92, v93
	s_waitcnt lgkmcnt(11)
	v_mfma_f32_32x32x16_bf16 v[114:129], v[174:177], v[158:161], v[114:129]
	ds_read_b64_tr_b16 v[86:87], v195 offset:29696
	ds_read_b64_tr_b16 v[88:89], v195 offset:30208
	s_waitcnt lgkmcnt(12)
	v_mfma_f32_32x32x16_bf16 v[98:113], v[166:169], v[158:161], v[98:113]
	v_add_f32_e32 v2, v96, v2
	v_add_f32_e32 v2, v97, v2
	v_add_f32_e32 v2, v66, v2
	v_add_f32_e32 v2, v67, v2
	v_cvt_pk_bf16_f32 v12, v94, v95
	v_cvt_pk_bf16_f32 v13, v96, v97
	ds_read_b64_tr_b16 v[90:91], v195 offset:26624
	ds_read_b64_tr_b16 v[92:93], v195 offset:27136
	v_add_f32_e32 v2, v68, v2
	v_add_f32_e32 v2, v69, v2
	v_add_f32_e32 v2, v70, v2
	v_add_f32_e32 v2, v71, v2
	v_cvt_pk_bf16_f32 v6, v66, v67
	v_cvt_pk_bf16_f32 v7, v68, v69
	s_waitcnt lgkmcnt(13)
	v_mfma_f32_32x32x16_bf16 v[114:129], v[142:145], v[154:157], v[114:129]
	ds_read_b64_tr_b16 v[66:67], v195 offset:30720
	ds_read_b64_tr_b16 v[68:69], v195 offset:31232
	s_waitcnt lgkmcnt(14)
	v_mfma_f32_32x32x16_bf16 v[98:113], v[138:141], v[154:157], v[98:113]
	v_add_f32_e32 v2, v72, v2
	v_add_f32_e32 v2, v73, v2
	v_add_f32_e32 v2, v74, v2
	v_add_f32_e32 v2, v75, v2
	v_cvt_pk_bf16_f32 v8, v70, v71
	v_cvt_pk_bf16_f32 v9, v72, v73
	ds_read_b64_tr_b16 v[70:71], v195 offset:27648
	ds_read_b64_tr_b16 v[72:73], v195 offset:28160
	v_add_f32_e32 v2, v76, v2
	v_add_f32_e32 v2, v77, v2
	v_add_f32_e32 v2, v78, v2
	v_add_f32_e32 v94, v79, v2
	v_cvt_pk_bf16_f32 v2, v74, v75
	v_cvt_pk_bf16_f32 v3, v76, v77
	s_waitcnt lgkmcnt(14)
	v_mfma_f32_32x32x16_bf16 v[114:129], v[134:137], v[150:153], v[114:129]
	ds_read_b64_tr_b16 v[74:75], v195 offset:31744
	ds_read_b64_tr_b16 v[76:77], v195 offset:32256
	v_mfma_f32_32x32x16_bf16 v[98:113], v[130:133], v[150:153], v[98:113]
	v_add_f32_e32 v4, v80, v94
	v_add_f32_e32 v4, v81, v4
	v_add_f32_e32 v195, 0, v4
	v_cvt_pk_bf16_f32 v4, v78, v79
	v_cvt_pk_bf16_f32 v5, v80, v81
	s_add_u32 s31, s2, s16
	s_addc_u32 s34, s22, s17
	s_add_u32 s36, s31, 0xe520300
	s_addc_u32 s37, s34, 0
	s_add_i32 s30, s29, s26
	s_mov_b32 s35, m0
	s_mov_b32 m0, s30
	s_nop 0
	global_load_lds_dwordx4 v193, s[36:37]
	s_mov_b32 m0, s35
	s_add_u32 s35, s23, s16
	s_addc_u32 s36, s24, s17
	s_add_u32 s38, s35, 0xe491100
	s_addc_u32 s39, s36, 0
	s_add_i32 s30, s28, s20
	s_mov_b32 s37, m0
	s_mov_b32 m0, s30
	s_nop 0
	global_load_lds_dwordx4 v192, s[38:39]
	s_mov_b32 m0, s37
	s_waitcnt lgkmcnt(14)
; #define WAIT_BAR(N) asm volatile("s_waitcnt vmcnt(" #N ") lgkmcnt(0)\n\ts_barrier" ::: "memory")
; #define RESC() do { if (resc) { asm volatile("s_waitcnt lgkmcnt(0)" ::: "memory"); \
;       _Pragma("unroll") for (int d_ = 0; d_ < 2; ++d_) _Pragma("unroll") for (int r = 0; r < 16; ++r) o[d_][r] *= wsf[crow(r, hi)]; } } while (0)
; #define ROT() do { sl_prev = sl_cur; sl_cur = sl_next; sl_next = (sl_next == (NSLOT - 1) * SLOTB) ? 0 : sl_next + SLOTB; } while (0)
;     ...
;     int t = 1;
;     for (; t + 5 < NT; t += 2) {
;         STEP(pB0, pB1, pA0, pA1, t, true, true, true);     WAIT_BAR(2); RESC(); ROT();
;         STEP(pA0, pA1, pB0, pB1, t + 1, true, true, true); WAIT_BAR(2); RESC(); ROT();
	v_mfma_f32_32x32x16_bf16 v[18:33], v[146:149], v[182:185], v[18:33]
	v_exp_f32_e32 v114, v114
	v_exp_f32_e32 v115, v115
	v_exp_f32_e32 v116, v116
	v_exp_f32_e32 v117, v117
	s_waitcnt lgkmcnt(12)
	v_mfma_f32_32x32x16_bf16 v[34:49], v[146:149], v[178:181], v[34:49]
	v_exp_f32_e32 v118, v118
	v_exp_f32_e32 v119, v119
	v_exp_f32_e32 v120, v120
	v_exp_f32_e32 v121, v121
	v_add_u32_e32 v94, s28, v191
	ds_read_b128 v[78:81], v94
	ds_read_b128 v[134:137], v94 offset:512
	s_waitcnt lgkmcnt(12)
	v_mfma_f32_32x32x16_bf16 v[18:33], v[10:13], v[82:85], v[18:33]
	v_exp_f32_e32 v122, v122
	v_exp_f32_e32 v123, v123
	v_exp_f32_e32 v124, v124
	v_exp_f32_e32 v125, v125
	ds_read_b128 v[138:141], v94 offset:2048
	ds_read_b128 v[142:145], v94 offset:2560
	s_waitcnt lgkmcnt(12)
	v_mfma_f32_32x32x16_bf16 v[34:49], v[10:13], v[86:89], v[34:49]
	v_exp_f32_e32 v126, v126
	v_exp_f32_e32 v127, v127
	v_exp_f32_e32 v128, v128
	v_exp_f32_e32 v129, v129
	ds_read_b128 v[166:169], v94 offset:4096
	ds_read_b128 v[170:173], v94 offset:4608
	s_waitcnt lgkmcnt(12)
	v_mfma_f32_32x32x16_bf16 v[18:33], v[6:9], v[90:93], v[18:33]
	v_exp_f32_e32 v98, v98
	v_exp_f32_e32 v99, v99
	v_exp_f32_e32 v100, v100
	v_exp_f32_e32 v101, v101
	ds_read_b128 v[174:177], v94 offset:6144
	ds_read_b128 v[130:133], v94 offset:6656
	s_waitcnt lgkmcnt(12)
	v_mfma_f32_32x32x16_bf16 v[34:49], v[6:9], v[66:69], v[34:49]
	v_exp_f32_e32 v102, v102
	v_exp_f32_e32 v103, v103
	v_exp_f32_e32 v104, v104
	v_exp_f32_e32 v105, v105
	s_waitcnt lgkmcnt(10)
	v_mfma_f32_32x32x16_bf16 v[18:33], v[2:5], v[70:73], v[18:33]
	v_exp_f32_e32 v106, v106
	v_exp_f32_e32 v107, v107
	v_exp_f32_e32 v108, v108
	v_exp_f32_e32 v109, v109
	s_waitcnt lgkmcnt(8)
	v_mfma_f32_32x32x16_bf16 v[34:49], v[2:5], v[74:77], v[34:49]
	v_exp_f32_e32 v110, v110
	v_exp_f32_e32 v111, v111
	v_exp_f32_e32 v112, v112
	v_exp_f32_e32 v113, v113
	s_waitcnt vmcnt(2) lgkmcnt(0)
	s_barrier
	s_add_i32 s30, s28, 0x2000
	s_cmpk_lg_i32 s28, 0x4000
	s_cselect_b32 s30, s30, 0
	v_add_u32_e32 v196, s29, v190
	ds_read_b64_tr_b16 v[178:179], v196 offset:24576
	ds_read_b64_tr_b16 v[180:181], v196 offset:25088
	s_waitcnt lgkmcnt(9)
	v_mfma_f32_32x32x16_bf16 v[82:97], v[78:81], v[162:165], v[50:65]
	v_add_f32_e32 v2, v114, v115
	v_add_f32_e32 v2, v116, v2
	v_add_f32_e32 v2, v117, v2
	v_add_f32_e32 v2, v118, v2
	v_add_f32_e32 v2, v119, v2
	v_cvt_pk_bf16_f32 v146, v114, v115
	v_cvt_pk_bf16_f32 v147, v116, v117
	ds_read_b64_tr_b16 v[182:183], v196 offset:28672
	ds_read_b64_tr_b16 v[184:185], v196 offset:29184
	s_waitcnt lgkmcnt(10)
	v_mfma_f32_32x32x16_bf16 v[66:81], v[134:137], v[162:165], v[50:65]
	v_add_f32_e32 v2, v120, v2
	v_add_f32_e32 v2, v121, v2
	v_add_f32_e32 v2, v122, v2
	v_add_f32_e32 v2, v123, v2
	v_cvt_pk_bf16_f32 v148, v118, v119
	v_cvt_pk_bf16_f32 v149, v120, v121
	ds_read_b64_tr_b16 v[114:115], v196 offset:25600
	ds_read_b64_tr_b16 v[116:117], v196 offset:26112
	s_waitcnt lgkmcnt(11)
	v_mfma_f32_32x32x16_bf16 v[82:97], v[138:141], v[158:161], v[82:97]
	v_add_f32_e32 v2, v124, v2
	v_add_f32_e32 v2, v125, v2
	v_add_f32_e32 v2, v126, v2
	v_add_f32_e32 v2, v127, v2
	v_cvt_pk_bf16_f32 v10, v122, v123
	v_cvt_pk_bf16_f32 v11, v124, v125
	ds_read_b64_tr_b16 v[118:119], v196 offset:29696
	ds_read_b64_tr_b16 v[120:121], v196 offset:30208
	s_waitcnt lgkmcnt(12)
	v_mfma_f32_32x32x16_bf16 v[66:81], v[142:145], v[158:161], v[66:81]
	v_add_f32_e32 v2, v128, v2
	v_add_f32_e32 v2, v129, v2
	v_add_f32_e32 v2, v98, v2
	v_add_f32_e32 v2, v99, v2
	v_cvt_pk_bf16_f32 v12, v126, v127
	v_cvt_pk_bf16_f32 v13, v128, v129
	ds_read_b64_tr_b16 v[122:123], v196 offset:26624
	ds_read_b64_tr_b16 v[124:125], v196 offset:27136
	s_waitcnt lgkmcnt(13)
	v_mfma_f32_32x32x16_bf16 v[82:97], v[166:169], v[154:157], v[82:97]
	v_add_f32_e32 v2, v100, v2
	v_add_f32_e32 v2, v101, v2
	v_add_f32_e32 v2, v102, v2
	v_add_f32_e32 v2, v103, v2
	v_cvt_pk_bf16_f32 v6, v98, v99
	v_cvt_pk_bf16_f32 v7, v100, v101
	ds_read_b64_tr_b16 v[126:127], v196 offset:30720
	ds_read_b64_tr_b16 v[128:129], v196 offset:31232
	s_waitcnt lgkmcnt(14)
	v_mfma_f32_32x32x16_bf16 v[66:81], v[170:173], v[154:157], v[66:81]
	v_add_f32_e32 v2, v104, v2
	v_add_f32_e32 v2, v105, v2
	v_add_f32_e32 v2, v106, v2
	v_add_f32_e32 v2, v107, v2
	v_cvt_pk_bf16_f32 v8, v102, v103
	v_cvt_pk_bf16_f32 v9, v104, v105
	ds_read_b64_tr_b16 v[102:103], v196 offset:27648
	ds_read_b64_tr_b16 v[104:105], v196 offset:28160
	s_waitcnt lgkmcnt(14)
	v_mfma_f32_32x32x16_bf16 v[82:97], v[174:177], v[150:153], v[82:97]
	v_add_f32_e32 v2, v108, v2
	v_add_f32_e32 v2, v109, v2
	v_add_f32_e32 v2, v110, v2
	v_add_f32_e32 v98, v111, v2
	v_cvt_pk_bf16_f32 v2, v106, v107
	v_cvt_pk_bf16_f32 v3, v108, v109
	ds_read_b64_tr_b16 v[106:107], v196 offset:31744
	ds_read_b64_tr_b16 v[108:109], v196 offset:32256
	v_mfma_f32_32x32x16_bf16 v[66:81], v[130:133], v[150:153], v[66:81]
	v_add_f32_e32 v4, v112, v98
	v_add_f32_e32 v4, v113, v4
	v_add_f32_e32 v196, 0, v4
	v_cvt_pk_bf16_f32 v4, v110, v111
	v_cvt_pk_bf16_f32 v5, v112, v113
	s_add_u32 s38, s31, 0xe568300
	s_addc_u32 s39, s34, 0
	s_add_i32 s29, s28, s26
	s_mov_b32 s31, m0
	s_mov_b32 m0, s29
	s_nop 0
	global_load_lds_dwordx4 v193, s[38:39]
	s_mov_b32 m0, s31
	s_add_u32 s34, s35, 0xe4d9100
	s_addc_u32 s35, s36, 0
	s_add_i32 s29, s30, s20
	s_mov_b32 s31, m0
	s_mov_b32 m0, s29
	s_nop 0
	global_load_lds_dwordx4 v192, s[34:35]
	s_mov_b32 m0, s31
	s_waitcnt lgkmcnt(14)
	v_mfma_f32_32x32x16_bf16 v[18:33], v[146:149], v[178:181], v[18:33]
	v_exp_f32_e32 v82, v82
	v_exp_f32_e32 v83, v83
	v_exp_f32_e32 v84, v84
	v_exp_f32_e32 v85, v85
	s_waitcnt lgkmcnt(12)
; #define WAIT_BAR(N) asm volatile("s_waitcnt vmcnt(" #N ") lgkmcnt(0)\n\ts_barrier" ::: "memory")
; #define RESC() do { if (resc) { asm volatile("s_waitcnt lgkmcnt(0)" ::: "memory"); \
;       _Pragma("unroll") for (int d_ = 0; d_ < 2; ++d_) _Pragma("unroll") for (int r = 0; r < 16; ++r) o[d_][r] *= wsf[crow(r, hi)]; } } while (0)
; #define ROT() do { sl_prev = sl_cur; sl_cur = sl_next; sl_next = (sl_next == (NSLOT - 1) * SLOTB) ? 0 : sl_next + SLOTB; } while (0)
; #define ENDW(tt) do { if ((tt) + 3 < NT) { WAIT_BAR(2); } else if ((tt) + 2 < NT) { WAIT_BAR(1); } else { WAIT_BAR(0); } } while (0)
;     ...
;     int t = 1;
;     for (; t + 5 < NT; t += 2) {
;         STEP(pB0, pB1, pA0, pA1, t, true, true, true);     WAIT_BAR(2); RESC(); ROT();
;         STEP(pA0, pA1, pB0, pB1, t + 1, true, true, true); WAIT_BAR(2); RESC(); ROT();
;     }
;     ...
;     for (; t + 1 < NT; t += 2) {
;         STEP(pB0, pB1, pA0, pA1, t, (t + 3 < NT), (t + 1 < NT), (t + 1 < NT));         ENDW(t);     RESC(); ROT();
	v_mfma_f32_32x32x16_bf16 v[34:49], v[146:149], v[182:185], v[34:49]
	v_exp_f32_e32 v86, v86
	v_exp_f32_e32 v87, v87
	v_exp_f32_e32 v88, v88
	v_exp_f32_e32 v89, v89
	v_add_u32_e32 v110, s30, v191
	ds_read_b128 v[98:101], v110
	ds_read_b128 v[170:173], v110 offset:512
	s_waitcnt lgkmcnt(12)
	v_mfma_f32_32x32x16_bf16 v[18:33], v[10:13], v[114:117], v[18:33]
	v_exp_f32_e32 v90, v90
	v_exp_f32_e32 v91, v91
	v_exp_f32_e32 v92, v92
	v_exp_f32_e32 v93, v93
	ds_read_b128 v[174:177], v110 offset:2048
	ds_read_b128 v[166:169], v110 offset:2560
	s_waitcnt lgkmcnt(12)
	v_mfma_f32_32x32x16_bf16 v[34:49], v[10:13], v[118:121], v[34:49]
	v_exp_f32_e32 v94, v94
	v_exp_f32_e32 v95, v95
	v_exp_f32_e32 v96, v96
	v_exp_f32_e32 v97, v97
	ds_read_b128 v[142:145], v110 offset:4096
	ds_read_b128 v[138:141], v110 offset:4608
	s_waitcnt lgkmcnt(12)
	v_mfma_f32_32x32x16_bf16 v[18:33], v[6:9], v[122:125], v[18:33]
	v_exp_f32_e32 v66, v66
	v_exp_f32_e32 v67, v67
	v_exp_f32_e32 v68, v68
	v_exp_f32_e32 v69, v69
	ds_read_b128 v[134:137], v110 offset:6144
	ds_read_b128 v[130:133], v110 offset:6656
	s_waitcnt lgkmcnt(12)
	v_mfma_f32_32x32x16_bf16 v[34:49], v[6:9], v[126:129], v[34:49]
	v_exp_f32_e32 v70, v70
	v_exp_f32_e32 v71, v71
	v_exp_f32_e32 v72, v72
	v_exp_f32_e32 v73, v73
	s_waitcnt lgkmcnt(10)
	v_mfma_f32_32x32x16_bf16 v[18:33], v[2:5], v[102:105], v[18:33]
	v_exp_f32_e32 v74, v74
	v_exp_f32_e32 v75, v75
	v_exp_f32_e32 v76, v76
	v_exp_f32_e32 v77, v77
	s_waitcnt lgkmcnt(8)
	v_mfma_f32_32x32x16_bf16 v[34:49], v[2:5], v[106:109], v[34:49]
	v_exp_f32_e32 v78, v78
	v_exp_f32_e32 v79, v79
	v_exp_f32_e32 v80, v80
	v_exp_f32_e32 v81, v81
	s_add_i32 s34, s30, 0x2000
	s_cmpk_lg_i32 s30, 0x4000
	s_mov_b32 s31, s28
	s_cselect_b32 s28, s34, 0
	s_add_i32 s27, s27, 2
	s_add_u32 s23, s23, 0x90000
	s_addc_u32 s24, s24, 0
	s_waitcnt vmcnt(2) lgkmcnt(0)
	s_barrier
	s_add_u32 s2, s2, 0x90000
	v_add_f32_e32 v2, v194, v195
	s_addc_u32 s22, s22, 0
	s_mov_b32 s29, s30
	v_add_f32_e32 v194, v2, v196
	s_cmpk_gt_u32 s27, 0x7c
	s_cbranch_scc0 .LBB0_876
	s_and_b32 s2, s25, 0x3fffffc0
	s_lshl_b32 s2, s2, 2
	s_add_i32 s2, s2, 0
	ds_read_b64_tr_b16 v[182:183], v190 offset:24576
	ds_read_b64_tr_b16 v[184:185], v190 offset:25088
	v_add_f32_e32 v2, v82, v83
	v_add_f32_e32 v2, v84, v2
	v_add_f32_e32 v2, v85, v2
	v_add_f32_e32 v2, v86, v2
	v_add_f32_e32 v2, v87, v2
	v_cvt_pk_bf16_f32 v146, v82, v83
	v_cvt_pk_bf16_f32 v147, v84, v85
	s_waitcnt lgkmcnt(9)
	v_mfma_f32_32x32x16_bf16 v[114:129], v[98:101], v[162:165], v[50:65]
	ds_read_b64_tr_b16 v[178:179], v190 offset:28672
	ds_read_b64_tr_b16 v[180:181], v190 offset:29184
	v_add_f32_e32 v2, v88, v2
	v_add_f32_e32 v2, v89, v2
	v_add_f32_e32 v2, v90, v2
	v_add_f32_e32 v2, v91, v2
	v_cvt_pk_bf16_f32 v148, v86, v87
	v_cvt_pk_bf16_f32 v149, v88, v89
	s_waitcnt lgkmcnt(10)
	v_mfma_f32_32x32x16_bf16 v[98:113], v[170:173], v[162:165], v[50:65]
	ds_read_b64_tr_b16 v[82:83], v190 offset:25600
	ds_read_b64_tr_b16 v[84:85], v190 offset:26112
	v_add_f32_e32 v2, v92, v2
	v_add_f32_e32 v2, v93, v2
	v_add_f32_e32 v2, v94, v2
	v_add_f32_e32 v2, v95, v2
	v_cvt_pk_bf16_f32 v10, v90, v91
	v_cvt_pk_bf16_f32 v11, v92, v93
	s_waitcnt lgkmcnt(11)
	v_mfma_f32_32x32x16_bf16 v[114:129], v[174:177], v[158:161], v[114:129]
	ds_read_b64_tr_b16 v[86:87], v190 offset:29696
	ds_read_b64_tr_b16 v[88:89], v190 offset:30208
	v_add_f32_e32 v2, v96, v2
	v_add_f32_e32 v2, v97, v2
	v_add_f32_e32 v2, v66, v2
	v_add_f32_e32 v2, v67, v2
	v_cvt_pk_bf16_f32 v12, v94, v95
	v_cvt_pk_bf16_f32 v13, v96, v97
	s_waitcnt lgkmcnt(12)
	v_mfma_f32_32x32x16_bf16 v[98:113], v[166:169], v[158:161], v[98:113]
	ds_read_b64_tr_b16 v[90:91], v190 offset:26624
	ds_read_b64_tr_b16 v[92:93], v190 offset:27136
	v_add_f32_e32 v2, v68, v2
	v_add_f32_e32 v2, v69, v2
	v_add_f32_e32 v2, v70, v2
	v_add_f32_e32 v2, v71, v2
	v_cvt_pk_bf16_f32 v6, v66, v67
	v_cvt_pk_bf16_f32 v7, v68, v69
	s_waitcnt lgkmcnt(13)
	v_mfma_f32_32x32x16_bf16 v[114:129], v[142:145], v[154:157], v[114:129]
	ds_read_b64_tr_b16 v[66:67], v190 offset:30720
	ds_read_b64_tr_b16 v[68:69], v190 offset:31232
	v_add_f32_e32 v2, v72, v2
	v_add_f32_e32 v2, v73, v2
	v_add_f32_e32 v2, v74, v2
	v_add_f32_e32 v2, v75, v2
	v_cvt_pk_bf16_f32 v8, v70, v71
	v_cvt_pk_bf16_f32 v9, v72, v73
	s_waitcnt lgkmcnt(14)
	v_mfma_f32_32x32x16_bf16 v[98:113], v[138:141], v[154:157], v[98:113]
	ds_read_b64_tr_b16 v[70:71], v190 offset:27648
	ds_read_b64_tr_b16 v[72:73], v190 offset:28160
	v_add_f32_e32 v2, v76, v2
	v_add_f32_e32 v2, v77, v2
	v_add_f32_e32 v2, v78, v2
	v_add_f32_e32 v94, v79, v2
	v_cvt_pk_bf16_f32 v2, v74, v75
	v_cvt_pk_bf16_f32 v3, v76, v77
	s_waitcnt lgkmcnt(14)
	v_mfma_f32_32x32x16_bf16 v[114:129], v[134:137], v[150:153], v[114:129]
	ds_read_b64_tr_b16 v[74:75], v190 offset:31744
	ds_read_b64_tr_b16 v[76:77], v190 offset:32256
	v_add_f32_e32 v4, v80, v94
	v_add_f32_e32 v4, v81, v4
	v_add_f32_e32 v94, 0, v4
	v_cvt_pk_bf16_f32 v4, v78, v79
	v_cvt_pk_bf16_f32 v5, v80, v81
	v_mfma_f32_32x32x16_bf16 v[98:113], v[130:133], v[150:153], v[98:113]
	s_add_u32 s16, s14, 0x2490000
	s_addc_u32 s17, s15, 0
	s_cmp_lg_u32 0, -1
	s_cselect_b32 s23, 0, 0
	s_add_i32 s22, s23, s21
	s_add_i32 s24, s22, 0x2000
	s_mov_b32 s25, m0
	s_mov_b32 m0, s24
	s_nop 0
	global_load_lds_dwordx4 v193, s[16:17]
	s_mov_b32 m0, s25
	s_add_u32 s24, s12, 0x2400000
	s_addc_u32 s25, s13, 0
	s_add_i32 s16, s23, 0xa000
	s_add_i32 s17, s21, s16
	s_mov_b32 s21, m0
	s_mov_b32 m0, s17
	s_nop 0
	global_load_lds_dwordx4 v192, s[24:25]
	s_mov_b32 m0, s21
	v_add_f32_e32 v194, v194, v94
	s_waitcnt lgkmcnt(14)
	v_mfma_f32_32x32x16_bf16 v[18:33], v[146:149], v[182:185], v[18:33]
	v_exp_f32_e32 v114, v114
	v_exp_f32_e32 v115, v115
	v_exp_f32_e32 v116, v116
	v_exp_f32_e32 v117, v117
	s_waitcnt lgkmcnt(12)
; #define WAIT_BAR(N) asm volatile("s_waitcnt vmcnt(" #N ") lgkmcnt(0)\n\ts_barrier" ::: "memory")
; #define RESC() do { if (resc) { asm volatile("s_waitcnt lgkmcnt(0)" ::: "memory"); \
;       _Pragma("unroll") for (int d_ = 0; d_ < 2; ++d_) _Pragma("unroll") for (int r = 0; r < 16; ++r) o[d_][r] *= wsf[crow(r, hi)]; } } while (0)
; #define ROT() do { sl_prev = sl_cur; sl_cur = sl_next; sl_next = (sl_next == (NSLOT - 1) * SLOTB) ? 0 : sl_next + SLOTB; } while (0)
; #define ENDW(tt) do { if ((tt) + 3 < NT) { WAIT_BAR(2); } else if ((tt) + 2 < NT) { WAIT_BAR(1); } else { WAIT_BAR(0); } } while (0)
;     ...
;     int t = 1;
;     for (; t + 5 < NT; t += 2) {
;         STEP(pB0, pB1, pA0, pA1, t, true, true, true);     WAIT_BAR(2); RESC(); ROT();
;         STEP(pA0, pA1, pB0, pB1, t + 1, true, true, true); WAIT_BAR(2); RESC(); ROT();
;     }
;     ...
;     for (; t + 1 < NT; t += 2) {
;         STEP(pB0, pB1, pA0, pA1, t, (t + 3 < NT), (t + 1 < NT), (t + 1 < NT));         ENDW(t);     RESC(); ROT();
;         STEP(pA0, pA1, pB0, pB1, t + 1, (t + 4 < NT), (t + 2 < NT), (t + 2 < NT));     ENDW(t + 1); RESC(); ROT();
	v_mfma_f32_32x32x16_bf16 v[34:49], v[146:149], v[178:181], v[34:49]
	v_exp_f32_e32 v118, v118
	v_exp_f32_e32 v119, v119
	v_exp_f32_e32 v120, v120
	v_exp_f32_e32 v121, v121
	ds_read_b128 v[78:81], v191 offset:16384
	ds_read_b128 v[94:97], v191 offset:16896
	s_waitcnt lgkmcnt(12)
	v_mfma_f32_32x32x16_bf16 v[18:33], v[10:13], v[82:85], v[18:33]
	v_exp_f32_e32 v122, v122
	v_exp_f32_e32 v123, v123
	v_exp_f32_e32 v124, v124
	v_exp_f32_e32 v125, v125
	ds_read_b128 v[166:169], v191 offset:18432
	ds_read_b128 v[170:173], v191 offset:18944
	s_waitcnt lgkmcnt(12)
	v_mfma_f32_32x32x16_bf16 v[34:49], v[10:13], v[86:89], v[34:49]
	v_exp_f32_e32 v126, v126
	v_exp_f32_e32 v127, v127
	v_exp_f32_e32 v128, v128
	v_exp_f32_e32 v129, v129
	ds_read_b128 v[174:177], v191 offset:20480
	ds_read_b128 v[178:181], v191 offset:20992
	s_waitcnt lgkmcnt(12)
	v_mfma_f32_32x32x16_bf16 v[18:33], v[6:9], v[90:93], v[18:33]
	v_exp_f32_e32 v98, v98
	v_exp_f32_e32 v99, v99
	v_exp_f32_e32 v100, v100
	v_exp_f32_e32 v101, v101
	ds_read_b128 v[90:93], v191 offset:22528
	ds_read_b128 v[82:85], v191 offset:23040
	s_waitcnt lgkmcnt(12)
	v_mfma_f32_32x32x16_bf16 v[34:49], v[6:9], v[66:69], v[34:49]
	v_exp_f32_e32 v102, v102
	v_exp_f32_e32 v103, v103
	v_exp_f32_e32 v104, v104
	v_exp_f32_e32 v105, v105
	s_waitcnt lgkmcnt(10)
	v_mfma_f32_32x32x16_bf16 v[18:33], v[2:5], v[70:73], v[18:33]
	v_exp_f32_e32 v106, v106
	v_exp_f32_e32 v107, v107
	v_exp_f32_e32 v108, v108
	v_exp_f32_e32 v109, v109
	s_waitcnt lgkmcnt(8)
	v_mfma_f32_32x32x16_bf16 v[34:49], v[2:5], v[74:77], v[34:49]
	v_exp_f32_e32 v110, v110
	v_exp_f32_e32 v111, v111
	v_exp_f32_e32 v112, v112
	v_exp_f32_e32 v113, v113
	s_waitcnt vmcnt(2) lgkmcnt(0)
	s_barrier
	ds_read_b64_tr_b16 v[182:183], v190 offset:32768
	ds_read_b64_tr_b16 v[184:185], v190 offset:33280
	v_add_f32_e32 v2, v114, v115
	v_add_f32_e32 v2, v116, v2
	v_add_f32_e32 v2, v117, v2
	v_add_f32_e32 v2, v118, v2
	v_add_f32_e32 v2, v119, v2
	v_cvt_pk_bf16_f32 v146, v114, v115
	v_cvt_pk_bf16_f32 v147, v116, v117
	s_waitcnt lgkmcnt(9)
	v_mfma_f32_32x32x16_bf16 v[130:145], v[78:81], v[162:165], v[50:65]
	ds_read_b64_tr_b16 v[114:115], v190 offset:36864
	ds_read_b64_tr_b16 v[116:117], v190 offset:37376
	s_waitcnt lgkmcnt(10)
	v_mfma_f32_32x32x16_bf16 v[66:81], v[94:97], v[162:165], v[50:65]
	v_add_f32_e32 v2, v120, v2
	v_add_f32_e32 v2, v121, v2
	v_add_f32_e32 v2, v122, v2
	v_add_f32_e32 v2, v123, v2
	v_cvt_pk_bf16_f32 v148, v118, v119
	v_cvt_pk_bf16_f32 v149, v120, v121
	ds_read_b64_tr_b16 v[86:87], v190 offset:33792
	ds_read_b64_tr_b16 v[88:89], v190 offset:34304
	v_add_f32_e32 v2, v124, v2
	v_add_f32_e32 v2, v125, v2
	v_add_f32_e32 v2, v126, v2
	v_add_f32_e32 v2, v127, v2
	v_cvt_pk_bf16_f32 v10, v122, v123
	v_cvt_pk_bf16_f32 v11, v124, v125
	s_waitcnt lgkmcnt(11)
	v_mfma_f32_32x32x16_bf16 v[130:145], v[166:169], v[158:161], v[130:145]
	ds_read_b64_tr_b16 v[94:95], v190 offset:37888
	ds_read_b64_tr_b16 v[96:97], v190 offset:38400
	s_waitcnt lgkmcnt(12)
	v_mfma_f32_32x32x16_bf16 v[66:81], v[170:173], v[158:161], v[66:81]
	v_add_f32_e32 v2, v128, v2
	v_add_f32_e32 v2, v129, v2
	v_add_f32_e32 v2, v98, v2
	v_add_f32_e32 v2, v99, v2
	v_cvt_pk_bf16_f32 v12, v126, v127
	v_cvt_pk_bf16_f32 v13, v128, v129
	ds_read_b64_tr_b16 v[118:119], v190 offset:34816
	ds_read_b64_tr_b16 v[120:121], v190 offset:35328
	v_add_f32_e32 v2, v100, v2
	v_add_f32_e32 v2, v101, v2
	v_add_f32_e32 v2, v102, v2
	v_add_f32_e32 v2, v103, v2
	v_cvt_pk_bf16_f32 v6, v98, v99
	v_cvt_pk_bf16_f32 v7, v100, v101
	s_waitcnt lgkmcnt(13)
	v_mfma_f32_32x32x16_bf16 v[130:145], v[174:177], v[154:157], v[130:145]
	ds_read_b64_tr_b16 v[122:123], v190 offset:38912
	ds_read_b64_tr_b16 v[124:125], v190 offset:39424
	s_waitcnt lgkmcnt(14)
	v_mfma_f32_32x32x16_bf16 v[66:81], v[178:181], v[154:157], v[66:81]
	v_add_f32_e32 v2, v104, v2
	v_add_f32_e32 v2, v105, v2
	v_add_f32_e32 v2, v106, v2
	v_add_f32_e32 v2, v107, v2
	v_cvt_pk_bf16_f32 v8, v102, v103
	v_cvt_pk_bf16_f32 v9, v104, v105
	ds_read_b64_tr_b16 v[102:103], v190 offset:35840
	ds_read_b64_tr_b16 v[104:105], v190 offset:36352
	v_add_f32_e32 v2, v108, v2
	v_add_f32_e32 v2, v109, v2
	v_add_f32_e32 v2, v110, v2
	v_add_f32_e32 v98, v111, v2
	v_cvt_pk_bf16_f32 v2, v106, v107
	v_cvt_pk_bf16_f32 v3, v108, v109
	s_waitcnt lgkmcnt(14)
	v_mfma_f32_32x32x16_bf16 v[130:145], v[90:93], v[150:153], v[130:145]
	ds_read_b64_tr_b16 v[90:91], v190 offset:39936
	ds_read_b64_tr_b16 v[92:93], v190 offset:40448
	v_mfma_f32_32x32x16_bf16 v[66:81], v[82:85], v[150:153], v[66:81]
	v_add_f32_e32 v4, v112, v98
	v_add_f32_e32 v4, v113, v4
	v_add_f32_e32 v82, 0, v4
	v_cvt_pk_bf16_f32 v4, v110, v111
	v_cvt_pk_bf16_f32 v5, v112, v113
	s_add_u32 s14, s14, 0x24d8000
	s_addc_u32 s15, s15, 0
	s_add_i32 s21, s22, 0x4000
	s_mov_b32 s23, m0
	s_mov_b32 m0, s21
	s_nop 0
	global_load_lds_dwordx4 v193, s[14:15]
	s_mov_b32 m0, s23
	s_add_u32 s14, s12, 0x2448000
	s_addc_u32 s15, s13, 0
	s_mov_b32 s21, m0
	s_mov_b32 m0, s20
	s_nop 0
	global_load_lds_dwordx4 v192, s[14:15]
	s_mov_b32 m0, s21
	v_add_f32_e32 v194, v194, v82
	s_waitcnt lgkmcnt(14)
	v_mfma_f32_32x32x16_bf16 v[18:33], v[146:149], v[182:185], v[18:33]
	v_exp_f32_e32 v130, v130
	v_exp_f32_e32 v131, v131
	v_exp_f32_e32 v132, v132
	v_exp_f32_e32 v133, v133
	s_waitcnt lgkmcnt(12)
	v_mfma_f32_32x32x16_bf16 v[34:49], v[146:149], v[114:117], v[34:49]
	v_exp_f32_e32 v134, v134
	v_exp_f32_e32 v135, v135
	v_exp_f32_e32 v136, v136
	v_exp_f32_e32 v137, v137
	ds_read_b128 v[82:85], v191
	ds_read_b128 v[106:109], v191 offset:512
	s_waitcnt lgkmcnt(12)
	v_mfma_f32_32x32x16_bf16 v[18:33], v[10:13], v[86:89], v[18:33]
	v_exp_f32_e32 v138, v138
	v_exp_f32_e32 v139, v139
	v_exp_f32_e32 v140, v140
	v_exp_f32_e32 v141, v141
	ds_read_b128 v[110:113], v191 offset:2048
	ds_read_b128 v[166:169], v191 offset:2560
	s_waitcnt lgkmcnt(12)
	v_mfma_f32_32x32x16_bf16 v[34:49], v[10:13], v[94:97], v[34:49]
	v_exp_f32_e32 v142, v142
	v_exp_f32_e32 v143, v143
	v_exp_f32_e32 v144, v144
	v_exp_f32_e32 v145, v145
	ds_read_b128 v[170:173], v191 offset:4096
	ds_read_b128 v[174:177], v191 offset:4608
	s_waitcnt lgkmcnt(12)
	v_mfma_f32_32x32x16_bf16 v[18:33], v[6:9], v[118:121], v[18:33]
	v_exp_f32_e32 v66, v66
	v_exp_f32_e32 v67, v67
	v_exp_f32_e32 v68, v68
	v_exp_f32_e32 v69, v69
	ds_read_b128 v[178:181], v191 offset:6144
	ds_read_b128 v[98:101], v191 offset:6656
	s_waitcnt lgkmcnt(12)
	v_mfma_f32_32x32x16_bf16 v[34:49], v[6:9], v[122:125], v[34:49]
	v_exp_f32_e32 v70, v70
	v_exp_f32_e32 v71, v71
	v_exp_f32_e32 v72, v72
	v_exp_f32_e32 v73, v73
	s_waitcnt lgkmcnt(10)
	v_mfma_f32_32x32x16_bf16 v[18:33], v[2:5], v[102:105], v[18:33]
	v_exp_f32_e32 v74, v74
	v_exp_f32_e32 v75, v75
	v_exp_f32_e32 v76, v76
	v_exp_f32_e32 v77, v77
	s_waitcnt lgkmcnt(8)
	v_mfma_f32_32x32x16_bf16 v[34:49], v[2:5], v[90:93], v[34:49]
	v_exp_f32_e32 v78, v78
	v_exp_f32_e32 v79, v79
	v_exp_f32_e32 v80, v80
	v_exp_f32_e32 v81, v81
	s_waitcnt vmcnt(2) lgkmcnt(0)
	s_barrier
; #define WAIT_BAR(N) asm volatile("s_waitcnt vmcnt(" #N ") lgkmcnt(0)\n\ts_barrier" ::: "memory")
; #define RESC() do { if (resc) { asm volatile("s_waitcnt lgkmcnt(0)" ::: "memory"); \
;       _Pragma("unroll") for (int d_ = 0; d_ < 2; ++d_) _Pragma("unroll") for (int r = 0; r < 16; ++r) o[d_][r] *= wsf[crow(r, hi)]; } } while (0)
; #define ROT() do { sl_prev = sl_cur; sl_cur = sl_next; sl_next = (sl_next == (NSLOT - 1) * SLOTB) ? 0 : sl_next + SLOTB; } while (0)
; #define ENDW(tt) do { if ((tt) + 3 < NT) { WAIT_BAR(2); } else if ((tt) + 2 < NT) { WAIT_BAR(1); } else { WAIT_BAR(0); } } while (0)
;     ...
;     int t = 1;
;     for (; t + 5 < NT; t += 2) {
;         STEP(pB0, pB1, pA0, pA1, t, true, true, true);     WAIT_BAR(2); RESC(); ROT();
;         STEP(pA0, pA1, pB0, pB1, t + 1, true, true, true); WAIT_BAR(2); RESC(); ROT();
;     }
;     ...
;     for (; t + 1 < NT; t += 2) {
;         STEP(pB0, pB1, pA0, pA1, t, (t + 3 < NT), (t + 1 < NT), (t + 1 < NT));         ENDW(t);     RESC(); ROT();
;         STEP(pA0, pA1, pB0, pB1, t + 1, (t + 4 < NT), (t + 2 < NT), (t + 2 < NT));     ENDW(t + 1); RESC(); ROT();
	ds_read_b64_tr_b16 v[102:103], v190 offset:40960
	ds_read_b64_tr_b16 v[104:105], v190 offset:41472
	v_add_f32_e32 v2, v130, v131
	v_add_f32_e32 v2, v132, v2
	v_add_f32_e32 v2, v133, v2
	v_add_f32_e32 v2, v134, v2
	v_add_f32_e32 v2, v135, v2
	v_cvt_pk_bf16_f32 v146, v130, v131
	v_cvt_pk_bf16_f32 v147, v132, v133
	s_waitcnt lgkmcnt(9)
	v_mfma_f32_32x32x16_bf16 v[114:129], v[82:85], v[162:165], v[50:65]
	ds_read_b64_tr_b16 v[130:131], v190 offset:45056
	ds_read_b64_tr_b16 v[132:133], v190 offset:45568
	v_add_f32_e32 v2, v136, v2
	v_add_f32_e32 v2, v137, v2
	v_add_f32_e32 v2, v138, v2
	v_add_f32_e32 v2, v139, v2
	v_cvt_pk_bf16_f32 v148, v134, v135
	v_cvt_pk_bf16_f32 v149, v136, v137
	s_waitcnt lgkmcnt(10)
	v_mfma_f32_32x32x16_bf16 v[82:97], v[106:109], v[162:165], v[50:65]
	ds_read_b64_tr_b16 v[106:107], v190 offset:41984
	ds_read_b64_tr_b16 v[108:109], v190 offset:42496
	v_add_f32_e32 v2, v140, v2
	v_add_f32_e32 v2, v141, v2
	v_add_f32_e32 v2, v142, v2
	v_add_f32_e32 v2, v143, v2
	v_cvt_pk_bf16_f32 v10, v138, v139
	v_cvt_pk_bf16_f32 v11, v140, v141
	s_waitcnt lgkmcnt(11)
	v_mfma_f32_32x32x16_bf16 v[114:129], v[110:113], v[158:161], v[114:129]
	ds_read_b64_tr_b16 v[110:111], v190 offset:46080
	ds_read_b64_tr_b16 v[112:113], v190 offset:46592
	v_add_f32_e32 v2, v144, v2
	v_add_f32_e32 v2, v145, v2
	v_add_f32_e32 v2, v66, v2
	v_add_f32_e32 v2, v67, v2
	v_cvt_pk_bf16_f32 v12, v142, v143
	v_cvt_pk_bf16_f32 v13, v144, v145
	s_waitcnt lgkmcnt(12)
	v_mfma_f32_32x32x16_bf16 v[82:97], v[166:169], v[158:161], v[82:97]
	ds_read_b64_tr_b16 v[134:135], v190 offset:43008
	ds_read_b64_tr_b16 v[136:137], v190 offset:43520
	v_add_f32_e32 v2, v68, v2
	v_add_f32_e32 v2, v69, v2
	v_add_f32_e32 v2, v70, v2
	v_add_f32_e32 v2, v71, v2
	v_cvt_pk_bf16_f32 v6, v66, v67
	v_cvt_pk_bf16_f32 v7, v68, v69
	s_waitcnt lgkmcnt(13)
	v_mfma_f32_32x32x16_bf16 v[114:129], v[170:173], v[154:157], v[114:129]
	ds_read_b64_tr_b16 v[66:67], v190 offset:47104
	ds_read_b64_tr_b16 v[68:69], v190 offset:47616
	v_add_f32_e32 v2, v72, v2
	v_add_f32_e32 v2, v73, v2
	v_add_f32_e32 v2, v74, v2
	v_add_f32_e32 v2, v75, v2
	v_cvt_pk_bf16_f32 v8, v70, v71
	v_cvt_pk_bf16_f32 v9, v72, v73
	s_waitcnt lgkmcnt(14)
	v_mfma_f32_32x32x16_bf16 v[82:97], v[174:177], v[154:157], v[82:97]
	ds_read_b64_tr_b16 v[70:71], v190 offset:44032
	ds_read_b64_tr_b16 v[72:73], v190 offset:44544
	v_add_f32_e32 v2, v76, v2
	v_add_f32_e32 v2, v77, v2
	v_add_f32_e32 v2, v78, v2
	v_add_f32_e32 v138, v79, v2
	v_cvt_pk_bf16_f32 v2, v74, v75
	v_cvt_pk_bf16_f32 v3, v76, v77
	s_waitcnt lgkmcnt(14)
	v_mfma_f32_32x32x16_bf16 v[114:129], v[178:181], v[150:153], v[114:129]
	ds_read_b64_tr_b16 v[74:75], v190 offset:48128
	ds_read_b64_tr_b16 v[76:77], v190 offset:48640
	v_add_f32_e32 v4, v80, v138
	v_add_f32_e32 v4, v81, v4
	v_mfma_f32_32x32x16_bf16 v[82:97], v[98:101], v[150:153], v[82:97]
	v_add_f32_e32 v98, 0, v4
	v_cvt_pk_bf16_f32 v4, v78, v79
	v_cvt_pk_bf16_f32 v5, v80, v81
	s_add_u32 s14, s12, 0x2490000
	s_addc_u32 s15, s13, 0
	s_add_i32 s22, s22, 0x8000
	s_mov_b32 s20, m0
	s_mov_b32 m0, s22
	s_nop 0
	global_load_lds_dwordx4 v192, s[14:15]
	s_mov_b32 m0, s20
	v_add_f32_e32 v182, v194, v98
	s_waitcnt lgkmcnt(14)
	v_mfma_f32_32x32x16_bf16 v[18:33], v[146:149], v[102:105], v[18:33]
	v_exp_f32_e32 v114, v114
	v_exp_f32_e32 v115, v115
	v_exp_f32_e32 v116, v116
	v_exp_f32_e32 v117, v117
	s_waitcnt lgkmcnt(12)
	v_mfma_f32_32x32x16_bf16 v[34:49], v[146:149], v[130:133], v[34:49]
	v_exp_f32_e32 v118, v118
	v_exp_f32_e32 v119, v119
	v_exp_f32_e32 v120, v120
	v_exp_f32_e32 v121, v121
	ds_read_b128 v[78:81], v191 offset:8192
	ds_read_b128 v[138:141], v191 offset:8704
	s_waitcnt lgkmcnt(12)
	v_mfma_f32_32x32x16_bf16 v[18:33], v[10:13], v[106:109], v[18:33]
	v_exp_f32_e32 v122, v122
	v_exp_f32_e32 v123, v123
	v_exp_f32_e32 v124, v124
	v_exp_f32_e32 v125, v125
	ds_read_b128 v[142:145], v191 offset:10240
	ds_read_b128 v[166:169], v191 offset:10752
	s_waitcnt lgkmcnt(12)
	v_mfma_f32_32x32x16_bf16 v[34:49], v[10:13], v[110:113], v[34:49]
	v_exp_f32_e32 v126, v126
	v_exp_f32_e32 v127, v127
	v_exp_f32_e32 v128, v128
	v_exp_f32_e32 v129, v129
	ds_read_b128 v[170:173], v191 offset:12288
	ds_read_b128 v[174:177], v191 offset:12800
	s_waitcnt lgkmcnt(12)
	v_mfma_f32_32x32x16_bf16 v[18:33], v[6:9], v[134:137], v[18:33]
	v_exp_f32_e32 v82, v82
	v_exp_f32_e32 v83, v83
	v_exp_f32_e32 v84, v84
	v_exp_f32_e32 v85, v85
	ds_read_b128 v[134:137], v191 offset:14336
	ds_read_b128 v[130:133], v191 offset:14848
	s_waitcnt lgkmcnt(12)
	v_mfma_f32_32x32x16_bf16 v[34:49], v[6:9], v[66:69], v[34:49]
	v_exp_f32_e32 v86, v86
	v_exp_f32_e32 v87, v87
	v_exp_f32_e32 v88, v88
	v_exp_f32_e32 v89, v89
	s_waitcnt lgkmcnt(10)
	v_mfma_f32_32x32x16_bf16 v[18:33], v[2:5], v[70:73], v[18:33]
	v_exp_f32_e32 v90, v90
	v_exp_f32_e32 v91, v91
	v_exp_f32_e32 v92, v92
	v_exp_f32_e32 v93, v93
	s_waitcnt lgkmcnt(8)
	v_mfma_f32_32x32x16_bf16 v[34:49], v[2:5], v[74:77], v[34:49]
	v_exp_f32_e32 v94, v94
	v_exp_f32_e32 v95, v95
	v_exp_f32_e32 v96, v96
	v_exp_f32_e32 v97, v97
	s_waitcnt vmcnt(1) lgkmcnt(0)
	s_barrier
; #define WAIT_BAR(N) asm volatile("s_waitcnt vmcnt(" #N ") lgkmcnt(0)\n\ts_barrier" ::: "memory")
; #define RESC() do { if (resc) { asm volatile("s_waitcnt lgkmcnt(0)" ::: "memory"); \
;       _Pragma("unroll") for (int d_ = 0; d_ < 2; ++d_) _Pragma("unroll") for (int r = 0; r < 16; ++r) o[d_][r] *= wsf[crow(r, hi)]; } } while (0)
; #define ROT() do { sl_prev = sl_cur; sl_cur = sl_next; sl_next = (sl_next == (NSLOT - 1) * SLOTB) ? 0 : sl_next + SLOTB; } while (0)
; #define ENDW(tt) do { if ((tt) + 3 < NT) { WAIT_BAR(2); } else if ((tt) + 2 < NT) { WAIT_BAR(1); } else { WAIT_BAR(0); } } while (0)
;     ...
;     int t = 1;
;     for (; t + 5 < NT; t += 2) {
;         STEP(pB0, pB1, pA0, pA1, t, true, true, true);     WAIT_BAR(2); RESC(); ROT();
;         STEP(pA0, pA1, pB0, pB1, t + 1, true, true, true); WAIT_BAR(2); RESC(); ROT();
;     }
;     ...
;     for (; t + 1 < NT; t += 2) {
;         STEP(pB0, pB1, pA0, pA1, t, (t + 3 < NT), (t + 1 < NT), (t + 1 < NT));         ENDW(t);     RESC(); ROT();
;         STEP(pA0, pA1, pB0, pB1, t + 1, (t + 4 < NT), (t + 2 < NT), (t + 2 < NT));     ENDW(t + 1); RESC(); ROT();
	ds_read_b64_tr_b16 v[178:179], v190 offset:24576
	ds_read_b64_tr_b16 v[180:181], v190 offset:25088
	v_add_f32_e32 v2, v114, v115
	v_add_f32_e32 v2, v116, v2
	v_add_f32_e32 v2, v117, v2
	v_add_f32_e32 v2, v118, v2
	v_add_f32_e32 v2, v119, v2
	v_cvt_pk_bf16_f32 v146, v114, v115
	v_cvt_pk_bf16_f32 v147, v116, v117
	s_waitcnt lgkmcnt(9)
	v_mfma_f32_32x32x16_bf16 v[98:113], v[78:81], v[162:165], v[50:65]
	ds_read_b64_tr_b16 v[114:115], v190 offset:28672
	ds_read_b64_tr_b16 v[116:117], v190 offset:29184
	s_waitcnt lgkmcnt(10)
	v_mfma_f32_32x32x16_bf16 v[66:81], v[138:141], v[162:165], v[50:65]
	v_add_f32_e32 v2, v120, v2
	v_add_f32_e32 v2, v121, v2
	v_add_f32_e32 v2, v122, v2
	v_add_f32_e32 v2, v123, v2
	v_cvt_pk_bf16_f32 v148, v118, v119
	v_cvt_pk_bf16_f32 v149, v120, v121
	ds_read_b64_tr_b16 v[118:119], v190 offset:25600
	ds_read_b64_tr_b16 v[120:121], v190 offset:26112
	v_add_f32_e32 v2, v124, v2
	v_add_f32_e32 v2, v125, v2
	v_add_f32_e32 v2, v126, v2
	v_add_f32_e32 v2, v127, v2
	v_cvt_pk_bf16_f32 v10, v122, v123
	v_cvt_pk_bf16_f32 v11, v124, v125
	s_waitcnt lgkmcnt(11)
	v_mfma_f32_32x32x16_bf16 v[98:113], v[142:145], v[158:161], v[98:113]
	ds_read_b64_tr_b16 v[122:123], v190 offset:29696
	ds_read_b64_tr_b16 v[124:125], v190 offset:30208
	s_waitcnt lgkmcnt(12)
	v_mfma_f32_32x32x16_bf16 v[66:81], v[166:169], v[158:161], v[66:81]
	v_add_f32_e32 v2, v128, v2
	v_add_f32_e32 v2, v129, v2
	v_add_f32_e32 v2, v82, v2
	v_add_f32_e32 v2, v83, v2
	v_cvt_pk_bf16_f32 v12, v126, v127
	v_cvt_pk_bf16_f32 v13, v128, v129
	ds_read_b64_tr_b16 v[138:139], v190 offset:26624
	ds_read_b64_tr_b16 v[140:141], v190 offset:27136
	v_add_f32_e32 v2, v84, v2
	v_add_f32_e32 v2, v85, v2
	v_add_f32_e32 v2, v86, v2
	v_add_f32_e32 v2, v87, v2
	v_cvt_pk_bf16_f32 v6, v82, v83
	v_cvt_pk_bf16_f32 v7, v84, v85
	s_waitcnt lgkmcnt(13)
	v_mfma_f32_32x32x16_bf16 v[98:113], v[170:173], v[154:157], v[98:113]
	ds_read_b64_tr_b16 v[82:83], v190 offset:30720
	ds_read_b64_tr_b16 v[84:85], v190 offset:31232
	s_waitcnt lgkmcnt(14)
	v_mfma_f32_32x32x16_bf16 v[66:81], v[174:177], v[154:157], v[66:81]
	v_add_f32_e32 v2, v88, v2
	v_add_f32_e32 v2, v89, v2
	v_add_f32_e32 v2, v90, v2
	v_add_f32_e32 v2, v91, v2
	v_cvt_pk_bf16_f32 v8, v86, v87
	v_cvt_pk_bf16_f32 v9, v88, v89
	ds_read_b64_tr_b16 v[86:87], v190 offset:27648
	ds_read_b64_tr_b16 v[88:89], v190 offset:28160
	v_add_f32_e32 v2, v92, v2
	v_add_f32_e32 v2, v93, v2
	v_add_f32_e32 v2, v94, v2
	v_add_f32_e32 v126, v95, v2
	v_cvt_pk_bf16_f32 v2, v90, v91
	v_cvt_pk_bf16_f32 v3, v92, v93
	s_waitcnt lgkmcnt(14)
	v_mfma_f32_32x32x16_bf16 v[98:113], v[134:137], v[150:153], v[98:113]
	ds_read_b64_tr_b16 v[90:91], v190 offset:31744
	ds_read_b64_tr_b16 v[92:93], v190 offset:32256
	v_mfma_f32_32x32x16_bf16 v[66:81], v[130:133], v[150:153], v[66:81]
	v_add_f32_e32 v4, v96, v126
	v_add_f32_e32 v4, v97, v4
	v_add_f32_e32 v126, 0, v4
	v_cvt_pk_bf16_f32 v4, v94, v95
	v_cvt_pk_bf16_f32 v5, v96, v97
	s_add_u32 s12, s12, 0x24d8000
	s_addc_u32 s13, s13, 0
	s_mov_b32 s14, m0
	s_mov_b32 m0, s17
	s_nop 0
	global_load_lds_dwordx4 v192, s[12:13]
	s_mov_b32 m0, s14
	v_add_f32_e32 v126, v182, v126
	s_waitcnt lgkmcnt(14)
	v_mfma_f32_32x32x16_bf16 v[18:33], v[146:149], v[178:181], v[18:33]
	v_exp_f32_e32 v98, v98
	v_exp_f32_e32 v99, v99
	v_exp_f32_e32 v100, v100
	v_exp_f32_e32 v101, v101
	s_waitcnt lgkmcnt(12)
	v_mfma_f32_32x32x16_bf16 v[34:49], v[146:149], v[114:117], v[34:49]
	v_exp_f32_e32 v102, v102
	v_exp_f32_e32 v103, v103
	v_exp_f32_e32 v104, v104
	v_exp_f32_e32 v105, v105
	ds_read_b128 v[128:131], v191 offset:16384
	ds_read_b128 v[132:135], v191 offset:16896
	s_waitcnt lgkmcnt(12)
	v_mfma_f32_32x32x16_bf16 v[18:33], v[10:13], v[118:121], v[18:33]
	v_exp_f32_e32 v106, v106
	v_exp_f32_e32 v107, v107
	v_exp_f32_e32 v108, v108
	v_exp_f32_e32 v109, v109
	ds_read_b128 v[142:145], v191 offset:18432
	ds_read_b128 v[166:169], v191 offset:18944
	s_waitcnt lgkmcnt(12)
	v_mfma_f32_32x32x16_bf16 v[34:49], v[10:13], v[122:125], v[34:49]
	v_exp_f32_e32 v110, v110
	v_exp_f32_e32 v111, v111
	v_exp_f32_e32 v112, v112
	v_exp_f32_e32 v113, v113
	ds_read_b128 v[170:173], v191 offset:20480
	ds_read_b128 v[174:177], v191 offset:20992
	s_waitcnt lgkmcnt(12)
	v_mfma_f32_32x32x16_bf16 v[18:33], v[6:9], v[138:141], v[18:33]
	v_exp_f32_e32 v66, v66
	v_exp_f32_e32 v67, v67
	v_exp_f32_e32 v68, v68
	v_exp_f32_e32 v69, v69
	ds_read_b128 v[136:139], v191 offset:22528
	ds_read_b128 v[122:125], v191 offset:23040
	s_waitcnt lgkmcnt(12)
	v_mfma_f32_32x32x16_bf16 v[34:49], v[6:9], v[82:85], v[34:49]
	v_exp_f32_e32 v70, v70
	v_exp_f32_e32 v71, v71
	v_exp_f32_e32 v72, v72
	v_exp_f32_e32 v73, v73
	s_waitcnt lgkmcnt(10)
	v_mfma_f32_32x32x16_bf16 v[18:33], v[2:5], v[86:89], v[18:33]
	v_exp_f32_e32 v74, v74
	v_exp_f32_e32 v75, v75
	v_exp_f32_e32 v76, v76
	v_exp_f32_e32 v77, v77
	s_waitcnt lgkmcnt(8)
	v_mfma_f32_32x32x16_bf16 v[34:49], v[2:5], v[90:93], v[34:49]
	v_exp_f32_e32 v78, v78
	v_exp_f32_e32 v79, v79
	v_exp_f32_e32 v80, v80
	v_exp_f32_e32 v81, v81
	s_waitcnt vmcnt(0) lgkmcnt(0)
	s_barrier
; #define RESC() do { if (resc) { asm volatile("s_waitcnt lgkmcnt(0)" ::: "memory"); \
;       _Pragma("unroll") for (int d_ = 0; d_ < 2; ++d_) _Pragma("unroll") for (int r = 0; r < 16; ++r) o[d_][r] *= wsf[crow(r, hi)]; } } while (0)
; #define PKW(P, B) cvtpk_s(P[B], P[B + 1])
;     ...
;     STEP(pB0, pB1, pA0, pA1, NT - 1, false, false, false); RESC();
;     { float sacc = pB0[0] + pB0[1]; _Pragma("unroll") for (int r = 2; r < 16; ++r) sacc += pB0[r]; _Pragma("unroll") for (int r = 0; r < 16; ++r) sacc += pB1[r]; l_reg += sacc;
;       pw0 = (u32x4){PKW(pB0, 0), PKW(pB0, 2), PKW(pB0, 4), PKW(pB0, 6)}; pw1 = (u32x4){PKW(pB0, 8), PKW(pB0, 10), PKW(pB0, 12), PKW(pB0, 14)}; pw2 = (u32x4){PKW(pB1, 0), PKW(pB1, 2), PKW(pB1, 4), PKW(pB1, 6)}; pw3 = (u32x4){PKW(pB1, 8), PKW(pB1, 10), PKW(pB1, 12), PKW(pB1, 14)};
	ds_read_b64_tr_b16 v[114:115], v190 offset:32768
	ds_read_b64_tr_b16 v[116:117], v190 offset:33280
	v_add_f32_e32 v2, v98, v99
	v_add_f32_e32 v2, v100, v2
	v_add_f32_e32 v2, v101, v2
	v_add_f32_e32 v2, v102, v2
	v_add_f32_e32 v2, v103, v2
	v_cvt_pk_bf16_f32 v146, v98, v99
	v_cvt_pk_bf16_f32 v147, v100, v101
	s_waitcnt lgkmcnt(9)
	v_mfma_f32_32x32x16_bf16 v[82:97], v[128:131], v[162:165], v[50:65]
	ds_read_b64_tr_b16 v[98:99], v190 offset:36864
	ds_read_b64_tr_b16 v[100:101], v190 offset:37376
	v_add_f32_e32 v2, v104, v2
	v_add_f32_e32 v2, v105, v2
	v_add_f32_e32 v2, v106, v2
	v_add_f32_e32 v2, v107, v2
	v_cvt_pk_bf16_f32 v148, v102, v103
	v_cvt_pk_bf16_f32 v149, v104, v105
	s_waitcnt lgkmcnt(10)
	v_mfma_f32_32x32x16_bf16 v[50:65], v[132:135], v[162:165], v[50:65]
	ds_read_b64_tr_b16 v[118:119], v190 offset:33792
	ds_read_b64_tr_b16 v[120:121], v190 offset:34304
	v_add_f32_e32 v2, v108, v2
	v_add_f32_e32 v2, v109, v2
	v_add_f32_e32 v2, v110, v2
	v_add_f32_e32 v2, v111, v2
	v_cvt_pk_bf16_f32 v10, v106, v107
	v_cvt_pk_bf16_f32 v11, v108, v109
	s_waitcnt lgkmcnt(11)
	v_mfma_f32_32x32x16_bf16 v[82:97], v[142:145], v[158:161], v[82:97]
	ds_read_b64_tr_b16 v[102:103], v190 offset:37888
	ds_read_b64_tr_b16 v[104:105], v190 offset:38400
	v_add_f32_e32 v2, v112, v2
	v_add_f32_e32 v2, v113, v2
	v_add_f32_e32 v2, v66, v2
	v_add_f32_e32 v2, v67, v2
	v_cvt_pk_bf16_f32 v12, v110, v111
	v_cvt_pk_bf16_f32 v13, v112, v113
	s_waitcnt lgkmcnt(12)
	v_mfma_f32_32x32x16_bf16 v[50:65], v[166:169], v[158:161], v[50:65]
	ds_read_b64_tr_b16 v[106:107], v190 offset:34816
	ds_read_b64_tr_b16 v[108:109], v190 offset:35328
	v_add_f32_e32 v2, v68, v2
	v_add_f32_e32 v2, v69, v2
	v_add_f32_e32 v2, v70, v2
	v_add_f32_e32 v2, v71, v2
	v_cvt_pk_bf16_f32 v6, v66, v67
	v_cvt_pk_bf16_f32 v7, v68, v69
	s_waitcnt lgkmcnt(13)
	v_mfma_f32_32x32x16_bf16 v[82:97], v[170:173], v[154:157], v[82:97]
	ds_read_b64_tr_b16 v[66:67], v190 offset:38912
	ds_read_b64_tr_b16 v[68:69], v190 offset:39424
	v_add_f32_e32 v2, v72, v2
	v_add_f32_e32 v2, v73, v2
	v_add_f32_e32 v2, v74, v2
	v_add_f32_e32 v2, v75, v2
	v_cvt_pk_bf16_f32 v8, v70, v71
	v_cvt_pk_bf16_f32 v9, v72, v73
	s_waitcnt lgkmcnt(14)
	v_mfma_f32_32x32x16_bf16 v[50:65], v[174:177], v[154:157], v[50:65]
	ds_read_b64_tr_b16 v[110:111], v190 offset:35840
	ds_read_b64_tr_b16 v[112:113], v190 offset:36352
	v_add_f32_e32 v2, v76, v2
	v_add_f32_e32 v2, v77, v2
	v_add_f32_e32 v2, v78, v2
	v_add_f32_e32 v127, v79, v2
	v_cvt_pk_bf16_f32 v2, v74, v75
	v_cvt_pk_bf16_f32 v3, v76, v77
	s_waitcnt lgkmcnt(14)
	v_mfma_f32_32x32x16_bf16 v[82:97], v[136:139], v[150:153], v[82:97]
	ds_read_b64_tr_b16 v[70:71], v190 offset:39936
	ds_read_b64_tr_b16 v[72:73], v190 offset:40448
	v_add_f32_e32 v4, v80, v127
	v_add_f32_e32 v4, v81, v4
	v_add_f32_e32 v74, 0, v4
	v_cvt_pk_bf16_f32 v4, v78, v79
	v_cvt_pk_bf16_f32 v5, v80, v81
	v_mfma_f32_32x32x16_bf16 v[50:65], v[122:125], v[150:153], v[50:65]
	s_nop 3
	v_exp_f32_e32 v82, v82
	v_exp_f32_e32 v83, v83
	v_exp_f32_e32 v84, v84
	v_exp_f32_e32 v85, v85
	s_nop 0
	v_exp_f32_e32 v86, v86
	v_exp_f32_e32 v87, v87
	v_exp_f32_e32 v88, v88
	v_exp_f32_e32 v89, v89
	s_nop 0
	v_exp_f32_e32 v90, v90
	v_exp_f32_e32 v91, v91
	v_exp_f32_e32 v92, v92
	v_exp_f32_e32 v93, v93
	s_nop 0
	v_exp_f32_e32 v94, v94
	v_exp_f32_e32 v95, v95
	v_exp_f32_e32 v96, v96
	v_exp_f32_e32 v97, v97
	v_exp_f32_e32 v50, v50
	v_exp_f32_e32 v51, v51
	v_exp_f32_e32 v52, v52
	v_exp_f32_e32 v53, v53
	s_nop 0
	v_exp_f32_e32 v54, v54
	v_exp_f32_e32 v55, v55
	v_exp_f32_e32 v56, v56
	v_exp_f32_e32 v57, v57
	s_nop 0
	v_exp_f32_e32 v58, v58
	v_exp_f32_e32 v59, v59
	v_exp_f32_e32 v60, v60
	v_exp_f32_e32 v61, v61
	s_nop 0
	v_exp_f32_e32 v62, v62
	v_exp_f32_e32 v63, v63
	v_exp_f32_e32 v64, v64
	v_exp_f32_e32 v65, v65
	s_waitcnt lgkmcnt(14)
	v_mfma_f32_32x32x16_bf16 v[18:33], v[146:149], v[114:117], v[18:33]
	v_add_f32_e32 v75, v82, v83
	v_add_f32_e32 v75, v84, v75
	v_add_f32_e32 v75, v85, v75
	v_add_f32_e32 v75, v86, v75
	v_add_f32_e32 v75, v87, v75
	v_add_f32_e32 v75, v88, v75
	v_add_f32_e32 v75, v89, v75
	s_waitcnt lgkmcnt(12)
	v_mfma_f32_32x32x16_bf16 v[34:49], v[146:149], v[98:101], v[34:49]
	v_add_f32_e32 v75, v90, v75
	v_add_f32_e32 v75, v91, v75
	v_add_f32_e32 v75, v92, v75
	v_add_f32_e32 v75, v93, v75
	v_add_f32_e32 v75, v94, v75
	v_add_f32_e32 v75, v95, v75
	v_add_f32_e32 v75, v96, v75
	s_waitcnt lgkmcnt(10)
	v_mfma_f32_32x32x16_bf16 v[18:33], v[10:13], v[118:121], v[18:33]
	v_add_f32_e32 v75, v97, v75
	v_add_f32_e32 v75, v50, v75
	v_add_f32_e32 v75, v51, v75
	v_add_f32_e32 v75, v52, v75
	v_add_f32_e32 v75, v53, v75
	v_add_f32_e32 v75, v54, v75
	v_add_f32_e32 v75, v55, v75
	s_waitcnt lgkmcnt(8)
	v_mfma_f32_32x32x16_bf16 v[34:49], v[10:13], v[102:105], v[34:49]
	v_add_f32_e32 v75, v56, v75
	v_add_f32_e32 v75, v57, v75
	v_add_f32_e32 v75, v58, v75
	v_add_f32_e32 v75, v59, v75
	v_add_f32_e32 v75, v60, v75
	v_add_f32_e32 v75, v61, v75
	v_add_f32_e32 v75, v62, v75
	s_waitcnt lgkmcnt(6)
	v_mfma_f32_32x32x16_bf16 v[18:33], v[6:9], v[106:109], v[18:33]
	v_add_f32_e32 v75, v63, v75
	v_add_f32_e32 v75, v64, v75
	v_add_f32_e32 v75, v65, v75
	v_add_f32_e32 v74, v126, v74
	v_add_f32_e32 v74, v74, v75
	v_cvt_pk_bf16_f32 v76, v82, v83
	v_cvt_pk_bf16_f32 v77, v84, v85
	s_waitcnt lgkmcnt(4)
	v_mfma_f32_32x32x16_bf16 v[34:49], v[6:9], v[66:69], v[34:49]
	v_cvt_pk_bf16_f32 v78, v86, v87
	v_cvt_pk_bf16_f32 v79, v88, v89
	v_cvt_pk_bf16_f32 v10, v90, v91
	v_cvt_pk_bf16_f32 v11, v92, v93
	v_cvt_pk_bf16_f32 v12, v94, v95
	v_cvt_pk_bf16_f32 v13, v96, v97
	v_cvt_pk_bf16_f32 v6, v50, v51
	s_waitcnt lgkmcnt(2)
; __device__ __forceinline__ int crow(int r, int hi) { return (r & 3) + 8 * (r >> 2) + 4 * hi; }
; __device__ __forceinline__ unsigned cvtpk_s(float lo, float hi) { typedef __bf16 bf16x2_t __attribute__((ext_vector_type(2))); f32x2 v = {lo, hi}; bf16x2_t b = __builtin_convertvector(v, bf16x2_t); return __builtin_bit_cast(unsigned, b); }
; #define SBAR() __builtin_amdgcn_sched_barrier(0)
; #define PKW(P, B) cvtpk_s(P[B], P[B + 1])
; __device__ __forceinline__ void store_tile(const f32x16* o, const float* rli, bf16_t* stg, bf16_t* Ow, int pitch, float* ss, int lane, int r32, int hi) {
; #pragma unroll
;     for (int r = 0; r < 16; ++r) { const int orow = crow(r, hi);
; #pragma unroll
;         for (int d0 = 0; d0 < 2; ++d0) stg[orow * 64 + d0 * 32 + r32] = (bf16_t)(cvtpk_s(o[d0][r] * rli[r], 0.f) & 0xffffu); }
;     ...
;       pw0 = (u32x4){PKW(pB0, 0), PKW(pB0, 2), PKW(pB0, 4), PKW(pB0, 6)}; pw1 = (u32x4){PKW(pB0, 8), PKW(pB0, 10), PKW(pB0, 12), PKW(pB0, 14)}; pw2 = (u32x4){PKW(pB1, 0), PKW(pB1, 2), PKW(pB1, 4), PKW(pB1, 6)}; pw3 = (u32x4){PKW(pB1, 8), PKW(pB1, 10), PKW(pB1, 12), PKW(pB1, 14)};
;       SBAR(); const int vb0 = (int)(lds0 + LDS_V) + ((lane >> 4) & 1) * 32 + (lane & 3) * 8 + (4 * hi + ((lane & 15) >> 2)) * 64;
;       at::pv(o, vb0 + sl_cur, PAF(0), PAF(1), PAF(2), PAF(3)); }
;     ...
;     { auto rr = __builtin_amdgcn_permlane32_swap(__float_as_uint(l_reg), __float_as_uint(l_reg), false, false); l_reg = __uint_as_float(rr[0]) + __uint_as_float(rr[1]); }
;     if (hi == 0) wsf[32 + r32] = l_reg; asm volatile("s_waitcnt lgkmcnt(0)" ::: "memory");
;     float rli[16];
; #pragma unroll
;     for (int r = 0; r < 16; ++r) rli[r] = __builtin_amdgcn_rcpf(wsf[32 + crow(r, hi)]);
	v_mfma_f32_32x32x16_bf16 v[18:33], v[2:5], v[110:113], v[18:33]
	v_cvt_pk_bf16_f32 v7, v52, v53
	v_cvt_pk_bf16_f32 v8, v54, v55
	v_cvt_pk_bf16_f32 v9, v56, v57
	v_cvt_pk_bf16_f32 v50, v58, v59
	v_cvt_pk_bf16_f32 v51, v60, v61
	v_cvt_pk_bf16_f32 v52, v62, v63
	v_cvt_pk_bf16_f32 v53, v64, v65
	s_waitcnt lgkmcnt(0)
	v_mfma_f32_32x32x16_bf16 v[34:49], v[2:5], v[70:73], v[34:49]
	v_add_u32_e32 v2, s16, v188
	v_add3_u32 v66, v2, v187, v189
	ds_read_b64_tr_b16 v[2:3],v66 offset:0
	ds_read_b64_tr_b16 v[4:5],v66 offset:512
	ds_read_b64_tr_b16 v[54:55],v66 offset:1024
	ds_read_b64_tr_b16 v[56:57],v66 offset:1536
	ds_read_b64_tr_b16 v[58:59],v66 offset:2048
	ds_read_b64_tr_b16 v[60:61],v66 offset:2560
	ds_read_b64_tr_b16 v[62:63],v66 offset:3072
	ds_read_b64_tr_b16 v[64:65],v66 offset:3584
	s_waitcnt lgkmcnt(0)
	s_nop 0
	v_mfma_f32_32x32x16_bf16 v[18:33], v[76:79], v[2:5], v[18:33]
	ds_read_b64_tr_b16 v[2:3],v66 offset:4096
	ds_read_b64_tr_b16 v[4:5],v66 offset:4608
	v_mfma_f32_32x32x16_bf16 v[18:33], v[10:13], v[54:57], v[18:33]
	ds_read_b64_tr_b16 v[54:55],v66 offset:5120
	ds_read_b64_tr_b16 v[56:57],v66 offset:5632
	v_mfma_f32_32x32x16_bf16 v[18:33], v[6:9], v[58:61], v[18:33]
	ds_read_b64_tr_b16 v[58:59],v66 offset:6144
	ds_read_b64_tr_b16 v[60:61],v66 offset:6656
	v_mfma_f32_32x32x16_bf16 v[18:33], v[50:53], v[62:65], v[18:33]
	ds_read_b64_tr_b16 v[62:63],v66 offset:7168
	ds_read_b64_tr_b16 v[64:65],v66 offset:7680
	s_waitcnt lgkmcnt(0)
	v_mfma_f32_32x32x16_bf16 v[34:49], v[76:79], v[2:5], v[34:49]
	v_mov_b32_e32 v2, v74
	s_nop 1
	v_permlane32_swap_b32_e32 v74, v2
	v_cmp_gt_u32_e32 vcc, 32, v15
	v_mfma_f32_32x32x16_bf16 v[34:49], v[10:13], v[54:57], v[34:49]
	v_mfma_f32_32x32x16_bf16 v[34:49], v[6:9], v[58:61], v[34:49]
	v_mfma_f32_32x32x16_bf16 v[34:49], v[50:53], v[62:65], v[34:49]
	s_setprio 0
	s_and_saveexec_b64 s[12:13], vcc
	v_add_f32_e32 v2, v74, v2
	v_lshl_add_u32 v3, v17, 2, s2
	ds_write_b32 v3, v2 offset:49280
	s_or_b64 exec, exec, s[12:13]
	s_waitcnt lgkmcnt(0)
	v_lshl_add_u32 v10, v186, 4, s2
	ds_read_b128 v[2:5], v10 offset:49280
	ds_read_b128 v[6:9], v10 offset:49312
	s_lshl_b64 s[12:13], s[4:5], 11
	s_add_u32 s10, s10, s12
	s_addc_u32 s11, s11, s13
	s_lshl_b64 s[4:5], s[4:5], 4
	s_add_u32 s8, s8, s4
	s_waitcnt lgkmcnt(1)
	v_rcp_f32_e32 v11, v2
	s_addc_u32 s2, s9, s5
	s_add_u32 s6, s10, s6
	s_addc_u32 s7, s11, s7
	s_lshl_b32 s4, s19, 12
	v_rcp_f32_e32 v12, v3
	v_rcp_f32_e32 v13, v4
	v_rcp_f32_e32 v50, v5
	s_waitcnt lgkmcnt(0)
	v_rcp_f32_e32 v51, v6
	ds_read_b128 v[2:5], v10 offset:49344
	v_rcp_f32_e32 v52, v7
	v_rcp_f32_e32 v53, v8
	v_rcp_f32_e32 v54, v9
	ds_read_b128 v[6:9], v10 offset:49376
	s_add_i32 s9, s4, 0
	v_mul_f32_e32 v10, v18, v11
	v_lshlrev_b32_e32 v0, 1, v0
	v_lshlrev_b32_e32 v17, 1, v17
	v_cvt_pk_bf16_f32 v10, v10, s0
	v_add3_u32 v0, s9, v0, v17
	ds_write_b16 v0, v10 offset:51200
	v_mul_f32_e32 v10, v34, v11
	v_cvt_pk_bf16_f32 v10, v10, s0
	ds_write_b16 v0, v10 offset:51264
	v_mul_f32_e32 v10, v19, v12
	v_cvt_pk_bf16_f32 v10, v10, s0
	ds_write_b16 v0, v10 offset:51328
	v_mul_f32_e32 v10, v35, v12
	v_cvt_pk_bf16_f32 v10, v10, s0
	ds_write_b16 v0, v10 offset:51392
	v_mul_f32_e32 v10, v20, v13
	v_cvt_pk_bf16_f32 v10, v10, s0
	ds_write_b16 v0, v10 offset:51456
	v_mul_f32_e32 v10, v36, v13
	v_cvt_pk_bf16_f32 v10, v10, s0
	ds_write_b16 v0, v10 offset:51520
	v_mul_f32_e32 v10, v21, v50
	v_cvt_pk_bf16_f32 v10, v10, s0
	ds_write_b16 v0, v10 offset:51584
	v_mul_f32_e32 v10, v37, v50
	v_cvt_pk_bf16_f32 v10, v10, s0
	ds_write_b16 v0, v10 offset:51648
	v_mul_f32_e32 v10, v22, v51
	v_cvt_pk_bf16_f32 v10, v10, s0
	ds_write_b16 v0, v10 offset:52224
	v_mul_f32_e32 v10, v38, v51
	v_cvt_pk_bf16_f32 v10, v10, s0
	ds_write_b16 v0, v10 offset:52288
	v_mul_f32_e32 v10, v23, v52
	v_cvt_pk_bf16_f32 v10, v10, s0
	ds_write_b16 v0, v10 offset:52352
	v_mul_f32_e32 v10, v39, v52
	v_cvt_pk_bf16_f32 v10, v10, s0
	ds_write_b16 v0, v10 offset:52416
	v_mul_f32_e32 v10, v24, v53
	v_cvt_pk_bf16_f32 v10, v10, s0
	ds_write_b16 v0, v10 offset:52480
	v_mul_f32_e32 v10, v40, v53
	v_cvt_pk_bf16_f32 v10, v10, s0
	s_waitcnt lgkmcnt(14)
; __device__ __forceinline__ int crow(int r, int hi) { return (r & 3) + 8 * (r >> 2) + 4 * hi; }
; __device__ __forceinline__ unsigned cvtpk_s(float lo, float hi) { typedef __bf16 bf16x2_t __attribute__((ext_vector_type(2))); f32x2 v = {lo, hi}; bf16x2_t b = __builtin_convertvector(v, bf16x2_t); return __builtin_bit_cast(unsigned, b); }
; __device__ __forceinline__ void store_tile(const f32x16* o, const float* rli, bf16_t* stg, bf16_t* Ow, int pitch, float* ss, int lane, int r32, int hi) {
; #pragma unroll
;     for (int r = 0; r < 16; ++r) { const int orow = crow(r, hi);
; #pragma unroll
;         for (int d0 = 0; d0 < 2; ++d0) stg[orow * 64 + d0 * 32 + r32] = (bf16_t)(cvtpk_s(o[d0][r] * rli[r], 0.f) & 0xffffu); }
;     asm volatile("s_waitcnt lgkmcnt(0)" ::: "memory");
; #pragma unroll
;     for (int i = 0; i < 4; ++i) { const int row = i * 8 + (lane >> 3), ch = lane & 7; const u32x4 v = *(const u32x4*)(stg + row * 64 + ch * 8);
;         { const bf16_t* gp_ = Ow + (long)row * pitch + ch * 8; asm volatile("global_store_dwordx4 %0, %1, off sc0 sc1\n\ts_nop 1" :: "v"(gp_), "v"(v) : "memory"); }
;         float s = 0.f;
; #pragma unroll
;         for (int j = 0; j < 4; ++j) { const float a = __uint_as_float(v[j] << 16), b = __uint_as_float(v[j] & 0xffff0000u); s += a * a + b * b; }
;         s += __shfl_xor(s, 1); s += __shfl_xor(s, 2); s += __shfl_xor(s, 4);
;         if (ch == 0) atomicAdd(ss + (long)row * 4, s); }
;     asm volatile("s_waitcnt lgkmcnt(0)" ::: "memory");
; }
	v_rcp_f32_e32 v2, v2
	ds_write_b16 v0, v10 offset:52544
	v_mul_f32_e32 v10, v25, v54
	v_cvt_pk_bf16_f32 v10, v10, s0
	v_rcp_f32_e32 v3, v3
	ds_write_b16 v0, v10 offset:52608
	v_mul_f32_e32 v10, v41, v54
	v_cvt_pk_bf16_f32 v10, v10, s0
	ds_write_b16 v0, v10 offset:52672
	v_mul_f32_e32 v10, v26, v2
	v_mul_f32_e32 v2, v42, v2
	v_cvt_pk_bf16_f32 v2, v2, s0
	v_rcp_f32_e32 v4, v4
	ds_write_b16 v0, v2 offset:53312
	v_mul_f32_e32 v2, v27, v3
	v_cvt_pk_bf16_f32 v2, v2, s0
	ds_write_b16 v0, v2 offset:53376
	v_mul_f32_e32 v2, v43, v3
	v_cvt_pk_bf16_f32 v2, v2, s0
	v_rcp_f32_e32 v5, v5
	ds_write_b16 v0, v2 offset:53440
	v_mul_f32_e32 v2, v28, v4
	v_cvt_pk_bf16_f32 v2, v2, s0
	ds_write_b16 v0, v2 offset:53504
	v_mul_f32_e32 v2, v44, v4
	v_cvt_pk_bf16_f32 v2, v2, s0
	s_waitcnt lgkmcnt(14)
	v_rcp_f32_e32 v6, v6
	ds_write_b16 v0, v2 offset:53568
	v_mul_f32_e32 v2, v29, v5
	v_cvt_pk_bf16_f32 v2, v2, s0
	ds_write_b16 v0, v2 offset:53632
	v_mul_f32_e32 v2, v45, v5
	v_cvt_pk_bf16_f32 v2, v2, s0
	v_rcp_f32_e32 v7, v7
	ds_write_b16 v0, v2 offset:53696
	v_mul_f32_e32 v2, v30, v6
	v_cvt_pk_bf16_f32 v2, v2, s0
	ds_write_b16 v0, v2 offset:54272
	v_mul_f32_e32 v2, v46, v6
	v_cvt_pk_bf16_f32 v2, v2, s0
	v_rcp_f32_e32 v8, v8
	ds_write_b16 v0, v2 offset:54336
	v_mul_f32_e32 v2, v31, v7
	v_cvt_pk_bf16_f32 v2, v2, s0
	ds_write_b16 v0, v2 offset:54400
	v_mul_f32_e32 v2, v47, v7
	v_cvt_pk_bf16_f32 v2, v2, s0
	v_rcp_f32_e32 v9, v9
	ds_write_b16 v0, v2 offset:54464
	v_mul_f32_e32 v2, v32, v8
	v_cvt_pk_bf16_f32 v2, v2, s0
	ds_write_b16 v0, v2 offset:54528
	v_mul_f32_e32 v2, v48, v8
	v_cvt_pk_bf16_f32 v2, v2, s0
	ds_write_b16 v0, v2 offset:54592
	v_mul_f32_e32 v2, v33, v9
	v_cvt_pk_bf16_f32 v2, v2, s0
	ds_write_b16 v0, v2 offset:54656
	v_mul_f32_e32 v2, v49, v9
	v_cvt_pk_bf16_f32 v10, v10, s0
	v_cvt_pk_bf16_f32 v2, v2, s0
	v_and_b32_e32 v6, 7, v14
	ds_write_b16 v0, v10 offset:53248
	ds_write_b16 v0, v2 offset:54720
	v_lshlrev_b32_e32 v0, 4, v6
	v_lshrrev_b32_e32 v7, 3, v15
	v_add_u32_e32 v8, s9, v0
	s_waitcnt lgkmcnt(0)
	v_lshl_add_u32 v2, v7, 7, v8
	ds_read_b128 v[12:15], v2 offset:51200
	s_lshl_b64 s[4:5], s[0:1], 11
	s_add_u32 s6, s6, s4
	s_addc_u32 s7, s7, s5
	s_lshl_b64 s[0:1], s[0:1], 4
	s_waitcnt lgkmcnt(0)
	v_and_b32_e32 v3, 0xffff0000, v12
	v_lshlrev_b32_e32 v2, 16, v12
	v_mul_f32_e32 v3, v3, v3
	v_and_b32_e32 v4, 0xffff0000, v13
	v_fmac_f32_e32 v3, v2, v2
	v_lshlrev_b32_e32 v2, 16, v13
	v_mul_f32_e32 v4, v4, v4
	v_fmac_f32_e32 v4, v2, v2
	v_add_f32_e32 v2, v3, v4
	v_and_b32_e32 v4, 0xffff0000, v14
	v_lshlrev_b32_e32 v3, 16, v14
	v_mul_f32_e32 v4, v4, v4
	v_fmac_f32_e32 v4, v3, v3
	v_add_f32_e32 v2, v4, v2
	v_and_b32_e32 v4, 0xffff0000, v15
	v_lshlrev_b32_e32 v3, 16, v15
	v_mul_f32_e32 v4, v4, v4
	v_fmac_f32_e32 v4, v3, v3
	v_and_b32_e32 v3, 64, v220
	v_add_f32_e32 v5, v4, v2
	v_xor_b32_e32 v2, 1, v220
	v_add_u32_e32 v10, 64, v3
	v_cmp_lt_i32_e32 vcc, v2, v10
	s_add_u32 s0, s8, s0
	s_addc_u32 s1, s2, s1
	v_cndmask_b32_e32 v2, v220, v2, vcc
	v_lshlrev_b32_e32 v4, 2, v2
	ds_bpermute_b32 v9, v4, v5
	v_lshl_add_u64 v[2:3], s[6:7], 0, v[0:1]
	v_xor_b32_e32 v0, 2, v220
	v_cmp_lt_i32_e32 vcc, v0, v10
	s_add_u32 s4, s0, 0x200008
	s_waitcnt lgkmcnt(0)
	v_add_f32_e32 v9, v5, v9
	v_cndmask_b32_e32 v0, v220, v0, vcc
	v_lshlrev_b32_e32 v5, 2, v0
	s_addc_u32 s5, s1, 0
	ds_bpermute_b32 v11, v5, v9
	s_mov_b64 s[0:1], 0x12e40500
	v_lshl_add_u64 v[2:3], v[2:3], 0, s[0:1]
	v_lshlrev_b32_e32 v0, 11, v7
	v_lshl_add_u64 v[18:19], v[2:3], 0, v[0:1]
	v_xor_b32_e32 v0, 4, v220
	v_cmp_lt_i32_e64 s[0:1], v0, v10
	v_cmp_eq_u32_e32 vcc, 0, v6
	s_waitcnt lgkmcnt(0)
	v_add_f32_e32 v9, v9, v11
	v_cndmask_b32_e64 v0, v220, v0, s[0:1]
	v_lshlrev_b32_e32 v6, 2, v0
	ds_bpermute_b32 v10, v6, v9
	global_store_dwordx4 v[18:19], v[12:15], off sc0 sc1
	s_nop 1
	s_and_saveexec_b64 s[0:1], vcc
	v_readlane_b32 s36, v253, 25
	v_readlane_b32 s37, v253, 26
	v_readlane_b32 s38, v253, 27
	v_readlane_b32 s39, v253, 28
	v_readlane_b32 s40, v253, 29
	v_readlane_b32 s41, v253, 30
	v_readlane_b32 s42, v253, 31
	v_readlane_b32 s43, v253, 32
	v_readlane_b32 s44, v253, 33
	v_readlane_b32 s45, v253, 34
	v_readlane_b32 s46, v253, 35
	v_readlane_b32 s47, v253, 36
	v_readlane_b32 s48, v253, 37
	v_readlane_b32 s49, v253, 38
	v_readlane_b32 s50, v253, 39
	v_readlane_b32 s51, v253, 40
	s_cbranch_execz .LBB0_881
	v_lshlrev_b32_e32 v0, 4, v7
	v_lshl_add_u64 v[12:13], s[4:5], 0, v[0:1]
	s_waitcnt lgkmcnt(0)
	v_add_f32_e32 v0, v9, v10
	flat_atomic_add_f32 v[12:13], v0
